# attention epilogue: output-gate loads issued before the merge barriers into unused registers
# speedup vs baseline: 1.0616x; 1.0001x over previous
; #define LAS __attribute__((address_space(3)))
; DI void attn_unit(const Params& p, int b, int h, int qb, LAS unsigned char* lds, int tid, int lane, int wave) {
;     ...
;     { const u32x2 sw_ = __builtin_amdgcn_permlane32_swap(__float_as_uint(lrow), __float_as_uint(lrow), false, false); lrow = __uint_as_float(sw_.x) + __uint_as_float(sw_.y); }
;     LAS float* MB = (LAS float*)(lds + AT_MB) + w4 * 66 * 64 + lane;
;     if (g == 1) {
; #pragma unroll
;         for (int i = 0; i < 4; ++i)
; #pragma unroll
;             for (int j = 0; j < 16; ++j) MB[(i * 16 + j) * 64] = o[i][j];
;         MB[64 * 64] = mrow; MB[65 * 64] = lrow;
;     }
;     __syncthreads();
;     if (g == 0) {
;         const float m1 = MB[64 * 64], l1 = MB[65 * 64];
;         const float m = fmaxf(mrow, m1);
;         const float a0 = __builtin_amdgcn_exp2f(mrow - m), a1 = __builtin_amdgcn_exp2f(m1 - m);
;         const float inv = 1.0f / (lrow * a0 + l1 * a1);
;         const size_t tok = tokb + qr0 + r;
;         const bf16_t* gp = Z + tok * ZLD + Z_MG + h * 128 + 4 * hh;
;         bf16_t* op = OB + tok * DM + 512 + h * 128 + 4 * hh;
;         u32x2 gw[4][4];
; #pragma unroll
;         for (int i = 0; i < 4; ++i)
; #pragma unroll
;             for (int q = 0; q < 4; ++q) gw[i][q] = *(const u32x2*)(gp + i * 32 + q * 8);
; #pragma unroll
.LBB0_440:
	v_mov_b32_e32 v0, v203
	s_mulk_i32 s20, 0x4200
	s_nop 0
	v_permlane32_swap_b32_e32 v203, v0
	s_add_i32 s0, s20, 0
	v_add_f32_e32 v68, v203, v0
	s_cmp_lg_u32 s21, 0
	s_cbranch_scc1 .Lgl1_skip
	v_lshlrev_b32_e32 v113, 12, v202
	s_lshl_b32 s1, s2, 8
	v_lshl_add_u32 v113, v182, 1, v113
	v_add_u32_e32 v113, s1, v113
	v_add_u32_e32 v113, 0x4600c00, v113
	global_load_dwordx2 v[114:115], v113, s[50:51]
	global_load_dwordx2 v[152:153], v113, s[50:51] offset:16
	global_load_dwordx2 v[154:155], v113, s[50:51] offset:32
	global_load_dwordx2 v[156:157], v113, s[50:51] offset:48
	global_load_dwordx2 v[158:159], v113, s[50:51] offset:64
	global_load_dwordx2 v[160:161], v113, s[50:51] offset:80
	global_load_dwordx2 v[162:163], v113, s[50:51] offset:96
	global_load_dwordx2 v[164:165], v113, s[50:51] offset:112
	global_load_dwordx2 v[166:167], v113, s[50:51] offset:128
	global_load_dwordx2 v[168:169], v113, s[50:51] offset:144
	global_load_dwordx2 v[170:171], v113, s[50:51] offset:160
	global_load_dwordx2 v[172:173], v113, s[50:51] offset:176
	global_load_dwordx2 v[174:175], v113, s[50:51] offset:192
	global_load_dwordx2 v[176:177], v113, s[50:51] offset:208
	global_load_dwordx2 v[178:179], v113, s[50:51] offset:224
	global_load_dwordx2 v[180:181], v113, s[50:51] offset:240
.Lgl1_skip:
	s_cmp_lg_u32 s21, 1
	v_lshl_add_u32 v104, v183, 2, s0
	s_barrier
	s_cbranch_scc1 .LBB0_442
	ds_write2st64_b32 v104, v50, v51 offset1:1
	ds_write2st64_b32 v104, v52, v53 offset0:2 offset1:3
	ds_write2st64_b32 v104, v54, v55 offset0:4 offset1:5
	ds_write2st64_b32 v104, v56, v57 offset0:6 offset1:7
	ds_write2st64_b32 v104, v58, v59 offset0:8 offset1:9
	ds_write2st64_b32 v104, v60, v61 offset0:10 offset1:11
	ds_write2st64_b32 v104, v62, v63 offset0:12 offset1:13
	ds_write2st64_b32 v104, v64, v65 offset0:14 offset1:15
	ds_write2st64_b32 v104, v34, v35 offset0:16 offset1:17
	ds_write2st64_b32 v104, v36, v37 offset0:18 offset1:19
	ds_write2st64_b32 v104, v38, v39 offset0:20 offset1:21
	ds_write2st64_b32 v104, v40, v41 offset0:22 offset1:23
	ds_write2st64_b32 v104, v42, v43 offset0:24 offset1:25
	ds_write2st64_b32 v104, v44, v45 offset0:26 offset1:27
	ds_write2st64_b32 v104, v46, v47 offset0:28 offset1:29
	ds_write2st64_b32 v104, v48, v49 offset0:30 offset1:31
	ds_write2st64_b32 v104, v18, v19 offset0:32 offset1:33
	ds_write2st64_b32 v104, v20, v21 offset0:34 offset1:35
	ds_write2st64_b32 v104, v22, v23 offset0:36 offset1:37
	ds_write2st64_b32 v104, v24, v25 offset0:38 offset1:39
	ds_write2st64_b32 v104, v26, v27 offset0:40 offset1:41
	ds_write2st64_b32 v104, v28, v29 offset0:42 offset1:43
	ds_write2st64_b32 v104, v30, v31 offset0:44 offset1:45
	ds_write2st64_b32 v104, v32, v33 offset0:46 offset1:47
	ds_write2st64_b32 v104, v2, v3 offset0:48 offset1:49
	ds_write2st64_b32 v104, v4, v5 offset0:50 offset1:51
	ds_write2st64_b32 v104, v6, v7 offset0:52 offset1:53
	ds_write2st64_b32 v104, v8, v9 offset0:54 offset1:55
	ds_write2st64_b32 v104, v10, v11 offset0:56 offset1:57
	ds_write2st64_b32 v104, v12, v13 offset0:58 offset1:59
	ds_write2st64_b32 v104, v14, v15 offset0:60 offset1:61
	ds_write2st64_b32 v104, v16, v17 offset0:62 offset1:63
	ds_write2st64_b32 v104, v204, v68 offset0:64 offset1:65
.LBB0_442:
	s_cmp_gt_u32 s3, 3
	s_waitcnt lgkmcnt(0)
	s_barrier
	s_cbranch_scc1 .LBB0_444
	ds_read2st64_b32 v[70:71], v104 offset0:64 offset1:65
	v_max_f32_e32 v0, v204, v204
	s_lshl_b32 s0, s2, 8
	s_mov_b32 s1, s93
	v_ashrrev_i32_e32 v183, 31, v182
	s_waitcnt lgkmcnt(0)
	v_max_f32_e32 v66, v70, v70
	v_max_f32_e32 v0, v0, v66
	v_sub_f32_e32 v66, v204, v0
	v_sub_f32_e32 v0, v70, v0
	v_exp_f32_e32 v66, v66
	v_exp_f32_e32 v67, v0
	v_mov_b32_e32 v69, v71
	v_lshlrev_b32_e32 v0, 12, v202
	v_lshlrev_b64 v[102:103], 1, v[182:183]
	v_pk_mul_f32 v[68:69], v[68:69], v[66:67]
	s_mov_b64 s[4:5], 0x4600c00
	v_add_f32_e32 v105, v68, v69
	v_lshl_add_u64 v[68:69], s[50:51], 0, v[0:1]
	v_lshl_add_u64 v[70:71], v[68:69], 0, s[0:1]
	v_lshlrev_b32_e32 v0, 11, v202
	v_lshl_add_u64 v[70:71], v[70:71], 0, v[102:103]
	v_sub_co_u32_e32 v72, vcc, 0, v0
	v_lshl_add_u64 v[106:107], v[70:71], 0, s[4:5]
	s_nop 0
	v_subb_co_u32_e64 v73, s[4:5], 0, 0, vcc
	v_lshl_add_u64 v[68:69], v[68:69], 0, v[72:73]
	v_lshl_add_u64 v[68:69], v[68:69], 0, s[0:1]
	s_mov_b32 s0, 0x4600000
	v_add_co_u32_e32 v70, vcc, s0, v70
	v_div_scale_f32 v0, s[0:1], v105, v105, 1.0
	s_nop 0
	v_addc_co_u32_e32 v71, vcc, 0, v71, vcc
	v_rcp_f32_e32 v106, v0
	v_lshl_add_u64 v[102:103], v[68:69], 0, v[102:103]
	s_mov_b64 s[0:1], 0xae00400
	v_lshl_add_u64 v[68:69], v[102:103], 0, s[0:1]
	v_fma_f32 v107, -v0, v106, 1.0
	v_fmac_f32_e32 v106, v107, v106
	v_div_scale_f32 v107, vcc, 1.0, v105, 1.0
	v_mul_f32_e32 v108, v107, v106
	v_fma_f32 v109, -v0, v108, v107
	v_fmac_f32_e32 v108, v109, v106
	v_fma_f32 v0, -v0, v108, v107
	v_div_fmas_f32 v0, v0, v106, v108
	ds_read2st64_b32 v[106:107], v104 offset1:1
	v_div_fixup_f32 v0, v0, v105, 1.0
	s_waitcnt vmcnt(0)
	v_lshlrev_b32_e32 v105, 16, v114
	v_and_b32_e32 v110, 0xffff0000, v114
	v_mul_f32_e32 v72, 0xbfb8aa3b, v105
	v_exp_f32_e32 v108, v72
	v_mov_b32_e32 v72, v67
	s_waitcnt lgkmcnt(0)
	v_pk_mul_f32 v[106:107], v[72:73], v[106:107] op_sel_hi:[0,1]
	v_pk_fma_f32 v[50:51], v[50:51], v[66:67], v[106:107] op_sel_hi:[1,0,1]
	v_mul_f32_e32 v67, 0xbfb8aa3b, v110
	v_exp_f32_e32 v109, v67
	v_pk_mul_f32 v[50:51], v[0:1], v[50:51] op_sel_hi:[0,1]
	v_pk_add_f32 v[106:107], v[108:109], 1.0 op_sel_hi:[1,0]
	s_nop 0
	v_rcp_f32_e32 v108, v107
	s_nop 0
	v_mul_f32_e32 v107, v110, v108
	v_rcp_f32_e32 v108, v106
	s_nop 0
	v_mul_f32_e32 v106, v105, v108
	v_lshlrev_b32_e32 v67, 16, v115
	v_pk_mul_f32 v[50:51], v[106:107], v[50:51]
	ds_read2st64_b32 v[106:107], v104 offset0:2 offset1:3
	v_and_b32_e32 v73, 0xffff0000, v115
	v_mul_f32_e32 v105, 0xbfb8aa3b, v67
	v_exp_f32_e32 v108, v105
	v_mul_f32_e32 v105, 0xbfb8aa3b, v73
	v_exp_f32_e32 v109, v105
	s_waitcnt lgkmcnt(0)
; DI unsigned pk2(float lo, float hi) { f32x2 v = {lo, hi}; return __builtin_bit_cast(unsigned, __builtin_convertvector(v, bf2_t)); }
; DI float bflo(unsigned w) { return __uint_as_float(w << 16); }
; DI float bfhi(unsigned w) { return __uint_as_float(w & 0xffff0000u); }
; DI void attn_unit(const Params& p, int b, int h, int qb, LAS unsigned char* lds, int tid, int lane, int wave) {
;     ...
; #pragma unroll
;         for (int i = 0; i < 4; ++i)
; #pragma unroll
;             for (int q = 0; q < 4; ++q) {
;                 float gv[4] = {bflo(gw[i][q].x), bfhi(gw[i][q].x), bflo(gw[i][q].y), bfhi(gw[i][q].y)}; float ov[4];
; #pragma unroll
;                 for (int e = 0; e < 4; ++e) { const float val = (o[i][q * 4 + e] * a0 + MB[(i * 16 + q * 4 + e) * 64] * a1) * inv; ov[e] = val * (gv[e] / (1.f + __expf(-gv[e]))); }
;                 *(u32x2*)(op + i * 32 + q * 8) = (u32x2){pk2(ov[0], ov[1]), pk2(ov[2], ov[3])};
;             }
	v_pk_mul_f32 v[106:107], v[72:73], v[106:107] op_sel_hi:[0,1]
	v_pk_fma_f32 v[52:53], v[52:53], v[66:67], v[106:107] op_sel_hi:[1,0,1]
	v_cvt_pk_bf16_f32 v116, v50, v51
	v_pk_add_f32 v[106:107], v[108:109], 1.0 op_sel_hi:[1,0]
	v_pk_mul_f32 v[52:53], v[0:1], v[52:53] op_sel_hi:[0,1]
	v_rcp_f32_e32 v108, v107
	s_nop 0
	v_mul_f32_e32 v107, v73, v108
	v_div_scale_f32 v73, s[0:1], v106, v106, v67
	v_rcp_f32_e32 v105, v73
	s_mov_b32 s0, 0xae00000
	v_fma_f32 v108, -v73, v105, 1.0
	v_fmac_f32_e32 v105, v108, v105
	v_div_scale_f32 v108, vcc, v67, v106, v67
	v_mul_f32_e32 v109, v108, v105
	v_fma_f32 v110, -v73, v109, v108
	v_fmac_f32_e32 v109, v110, v105
	v_fma_f32 v73, -v73, v109, v108
	v_div_fmas_f32 v73, v73, v105, v109
	v_div_fixup_f32 v106, v73, v106, v67
	v_pk_mul_f32 v[52:53], v[106:107], v[52:53]
	v_lshlrev_b32_e32 v67, 16, v152
	v_cvt_pk_bf16_f32 v117, v52, v53
	v_add_co_u32_e32 v52, vcc, s0, v102
	v_and_b32_e32 v73, 0xffff0000, v152
	s_nop 0
	v_addc_co_u32_e32 v53, vcc, 0, v103, vcc
	ds_read2st64_b32 v[50:51], v104 offset0:4 offset1:5
	v_mul_f32_e32 v52, 0xbfb8aa3b, v67
	v_mul_f32_e32 v53, 0xbfb8aa3b, v73
	v_exp_f32_e32 v52, v52
	v_exp_f32_e32 v53, v53
	s_waitcnt lgkmcnt(0)
	v_pk_mul_f32 v[50:51], v[72:73], v[50:51] op_sel_hi:[0,1]
	v_pk_fma_f32 v[50:51], v[54:55], v[66:67], v[50:51] op_sel_hi:[1,0,1]
	v_pk_add_f32 v[52:53], v[52:53], 1.0 op_sel_hi:[1,0]
	s_nop 0
	v_div_scale_f32 v54, s[0:1], v53, v53, v73
	v_rcp_f32_e32 v55, v54
	v_pk_mul_f32 v[50:51], v[0:1], v[50:51] op_sel_hi:[0,1]
	v_fma_f32 v100, -v54, v55, 1.0
	v_fmac_f32_e32 v55, v100, v55
	v_div_scale_f32 v100, vcc, v73, v53, v73
	v_mul_f32_e32 v102, v100, v55
	v_fma_f32 v103, -v54, v102, v100
	v_fmac_f32_e32 v102, v103, v55
	v_fma_f32 v54, -v54, v102, v100
	v_div_fmas_f32 v54, v54, v55, v102
	v_div_fixup_f32 v53, v54, v53, v73
	v_rcp_f32_e32 v55, v52
	s_nop 0
	v_mul_f32_e32 v52, v67, v55
	v_lshlrev_b32_e32 v67, 16, v153
	v_and_b32_e32 v73, 0xffff0000, v153
	v_pk_mul_f32 v[50:51], v[52:53], v[50:51]
	ds_read2st64_b32 v[52:53], v104 offset0:6 offset1:7
	v_mul_f32_e32 v54, 0xbfb8aa3b, v67
	v_mul_f32_e32 v55, 0xbfb8aa3b, v73
	v_exp_f32_e32 v54, v54
	v_exp_f32_e32 v55, v55
	s_waitcnt lgkmcnt(0)
	v_pk_mul_f32 v[52:53], v[72:73], v[52:53] op_sel_hi:[0,1]
	v_pk_fma_f32 v[52:53], v[56:57], v[66:67], v[52:53] op_sel_hi:[1,0,1]
	v_cvt_pk_bf16_f32 v118, v50, v51
	v_pk_add_f32 v[54:55], v[54:55], 1.0 op_sel_hi:[1,0]
	v_pk_mul_f32 v[52:53], v[0:1], v[52:53] op_sel_hi:[0,1]
	v_rcp_f32_e32 v57, v55
	s_nop 0
	v_mul_f32_e32 v55, v73, v57
	v_rcp_f32_e32 v57, v54
	s_nop 0
	v_mul_f32_e32 v54, v67, v57
	v_pk_mul_f32 v[52:53], v[54:55], v[52:53]
	v_lshlrev_b32_e32 v54, 16, v154
	v_and_b32_e32 v55, 0xffff0000, v154
	v_cvt_pk_bf16_f32 v119, v52, v53
	v_mul_f32_e32 v52, 0xbfb8aa3b, v54
	v_mul_f32_e32 v53, 0xbfb8aa3b, v55
	v_exp_f32_e32 v52, v52
	v_exp_f32_e32 v53, v53
	v_lshlrev_b32_e32 v150, 1, v182
	v_mov_b32_e32 v151, 0
	v_lshl_add_u64 v[148:149], v[150:151], 0, v[68:69]
	s_nop 1
	v_permlane32_swap_b32_e32 v116, v118
	v_permlane32_swap_b32_e32 v117, v119
	global_store_dwordx4 v[148:149], v[116:119], off
	ds_read2st64_b32 v[50:51], v104 offset0:8 offset1:9
	v_pk_add_f32 v[52:53], v[52:53], 1.0 op_sel_hi:[1,0]
	s_nop 0
	v_div_scale_f32 v56, s[0:1], v53, v53, v55
	v_rcp_f32_e32 v57, v56
	s_waitcnt lgkmcnt(0)
	v_pk_mul_f32 v[50:51], v[72:73], v[50:51] op_sel_hi:[0,1]
	v_pk_fma_f32 v[50:51], v[58:59], v[66:67], v[50:51] op_sel_hi:[1,0,1]
	v_fma_f32 v58, -v56, v57, 1.0
	v_fmac_f32_e32 v57, v58, v57
	v_div_scale_f32 v58, vcc, v55, v53, v55
	v_mul_f32_e32 v59, v58, v57
	v_fma_f32 v67, -v56, v59, v58
	v_fmac_f32_e32 v59, v67, v57
	v_fma_f32 v56, -v56, v59, v58
	v_div_fmas_f32 v56, v56, v57, v59
	v_div_fixup_f32 v53, v56, v53, v55
	v_div_scale_f32 v55, s[0:1], v52, v52, v54
	v_rcp_f32_e32 v56, v55
	v_pk_mul_f32 v[50:51], v[0:1], v[50:51] op_sel_hi:[0,1]
	v_fma_f32 v57, -v55, v56, 1.0
	v_fmac_f32_e32 v56, v57, v56
	v_div_scale_f32 v57, vcc, v54, v52, v54
	v_mul_f32_e32 v58, v57, v56
	v_fma_f32 v59, -v55, v58, v57
	v_fmac_f32_e32 v58, v59, v56
	v_fma_f32 v55, -v55, v58, v57
	v_div_fmas_f32 v55, v55, v56, v58
	v_lshlrev_b32_e32 v56, 16, v155
	v_and_b32_e32 v57, 0xffff0000, v155
	v_div_fixup_f32 v52, v55, v52, v54
	v_mul_f32_e32 v54, 0xbfb8aa3b, v56
	v_mul_f32_e32 v55, 0xbfb8aa3b, v57
	v_exp_f32_e32 v54, v54
	v_exp_f32_e32 v55, v55
	v_pk_mul_f32 v[50:51], v[52:53], v[50:51]
	ds_read2st64_b32 v[52:53], v104 offset0:10 offset1:11
	v_cvt_pk_bf16_f32 v120, v50, v51
	v_pk_add_f32 v[54:55], v[54:55], 1.0 op_sel_hi:[1,0]
	s_waitcnt lgkmcnt(0)
	v_pk_mul_f32 v[52:53], v[72:73], v[52:53] op_sel_hi:[0,1]
	v_div_scale_f32 v58, s[0:1], v55, v55, v57
	v_rcp_f32_e32 v59, v58
	v_pk_fma_f32 v[52:53], v[60:61], v[66:67], v[52:53] op_sel_hi:[1,0,1]
	v_fma_f32 v60, -v58, v59, 1.0
	v_fmac_f32_e32 v59, v60, v59
	v_div_scale_f32 v60, vcc, v57, v55, v57
	v_mul_f32_e32 v61, v60, v59
	v_fma_f32 v67, -v58, v61, v60
	v_fmac_f32_e32 v61, v67, v59
	v_fma_f32 v58, -v58, v61, v60
	v_div_fmas_f32 v58, v58, v59, v61
	v_div_fixup_f32 v55, v58, v55, v57
	v_div_scale_f32 v57, s[0:1], v54, v54, v56
	v_rcp_f32_e32 v58, v57
	v_pk_mul_f32 v[52:53], v[0:1], v[52:53] op_sel_hi:[0,1]
	v_fma_f32 v59, -v57, v58, 1.0
	v_fmac_f32_e32 v58, v59, v58
	v_div_scale_f32 v59, vcc, v56, v54, v56
	v_mul_f32_e32 v60, v59, v58
	v_fma_f32 v61, -v57, v60, v59
	v_fmac_f32_e32 v60, v61, v58
	v_fma_f32 v57, -v57, v60, v59
	v_div_fmas_f32 v57, v57, v58, v60
	v_div_fixup_f32 v54, v57, v54, v56
	v_pk_mul_f32 v[52:53], v[54:55], v[52:53]
	v_lshlrev_b32_e32 v54, 16, v156
	v_and_b32_e32 v55, 0xffff0000, v156
	v_cvt_pk_bf16_f32 v121, v52, v53
	v_mul_f32_e32 v52, 0xbfb8aa3b, v54
	v_mul_f32_e32 v53, 0xbfb8aa3b, v55
	v_exp_f32_e32 v52, v52
	v_exp_f32_e32 v53, v53
	ds_read2st64_b32 v[50:51], v104 offset0:12 offset1:13
	v_pk_add_f32 v[52:53], v[52:53], 1.0 op_sel_hi:[1,0]
	s_nop 0
	v_div_scale_f32 v56, s[0:1], v53, v53, v55
	v_rcp_f32_e32 v57, v56
	s_waitcnt lgkmcnt(0)
; DI unsigned pk2(float lo, float hi) { f32x2 v = {lo, hi}; return __builtin_bit_cast(unsigned, __builtin_convertvector(v, bf2_t)); }
; DI float bflo(unsigned w) { return __uint_as_float(w << 16); }
; DI float bfhi(unsigned w) { return __uint_as_float(w & 0xffff0000u); }
; DI void attn_unit(const Params& p, int b, int h, int qb, LAS unsigned char* lds, int tid, int lane, int wave) {
;     ...
; #pragma unroll
;         for (int i = 0; i < 4; ++i)
; #pragma unroll
;             for (int q = 0; q < 4; ++q) {
;                 float gv[4] = {bflo(gw[i][q].x), bfhi(gw[i][q].x), bflo(gw[i][q].y), bfhi(gw[i][q].y)}; float ov[4];
; #pragma unroll
;                 for (int e = 0; e < 4; ++e) { const float val = (o[i][q * 4 + e] * a0 + MB[(i * 16 + q * 4 + e) * 64] * a1) * inv; ov[e] = val * (gv[e] / (1.f + __expf(-gv[e]))); }
;                 *(u32x2*)(op + i * 32 + q * 8) = (u32x2){pk2(ov[0], ov[1]), pk2(ov[2], ov[3])};
;             }
	v_pk_mul_f32 v[50:51], v[72:73], v[50:51] op_sel_hi:[0,1]
	v_pk_fma_f32 v[50:51], v[62:63], v[66:67], v[50:51] op_sel_hi:[1,0,1]
	v_fma_f32 v58, -v56, v57, 1.0
	v_fmac_f32_e32 v57, v58, v57
	v_div_scale_f32 v58, vcc, v55, v53, v55
	v_mul_f32_e32 v59, v58, v57
	v_fma_f32 v60, -v56, v59, v58
	v_fmac_f32_e32 v59, v60, v57
	v_fma_f32 v56, -v56, v59, v58
	v_div_fmas_f32 v56, v56, v57, v59
	v_div_fixup_f32 v53, v56, v53, v55
	v_div_scale_f32 v55, s[0:1], v52, v52, v54
	v_rcp_f32_e32 v56, v55
	v_pk_mul_f32 v[50:51], v[0:1], v[50:51] op_sel_hi:[0,1]
	v_fma_f32 v57, -v55, v56, 1.0
	v_fmac_f32_e32 v56, v57, v56
	v_div_scale_f32 v57, vcc, v54, v52, v54
	v_mul_f32_e32 v58, v57, v56
	v_fma_f32 v59, -v55, v58, v57
	v_fmac_f32_e32 v58, v59, v56
	v_fma_f32 v55, -v55, v58, v57
	v_div_fmas_f32 v55, v55, v56, v58
	v_lshlrev_b32_e32 v56, 16, v157
	v_and_b32_e32 v57, 0xffff0000, v157
	v_div_fixup_f32 v52, v55, v52, v54
	v_mul_f32_e32 v54, 0xbfb8aa3b, v56
	v_mul_f32_e32 v55, 0xbfb8aa3b, v57
	v_exp_f32_e32 v54, v54
	v_exp_f32_e32 v55, v55
	v_pk_mul_f32 v[50:51], v[52:53], v[50:51]
	ds_read2st64_b32 v[52:53], v104 offset0:14 offset1:15
	v_cvt_pk_bf16_f32 v122, v50, v51
	v_pk_add_f32 v[54:55], v[54:55], 1.0 op_sel_hi:[1,0]
	s_waitcnt lgkmcnt(0)
	v_pk_mul_f32 v[52:53], v[72:73], v[52:53] op_sel_hi:[0,1]
	v_div_scale_f32 v58, s[0:1], v55, v55, v57
	v_rcp_f32_e32 v59, v58
	v_pk_fma_f32 v[52:53], v[64:65], v[66:67], v[52:53] op_sel_hi:[1,0,1]
	v_fma_f32 v60, -v58, v59, 1.0
	v_fmac_f32_e32 v59, v60, v59
	v_div_scale_f32 v60, vcc, v57, v55, v57
	v_mul_f32_e32 v61, v60, v59
	v_fma_f32 v62, -v58, v61, v60
	v_fmac_f32_e32 v61, v62, v59
	v_fma_f32 v58, -v58, v61, v60
	v_div_fmas_f32 v58, v58, v59, v61
	v_div_fixup_f32 v55, v58, v55, v57
	v_div_scale_f32 v57, s[0:1], v54, v54, v56
	v_rcp_f32_e32 v58, v57
	v_pk_mul_f32 v[52:53], v[0:1], v[52:53] op_sel_hi:[0,1]
	v_fma_f32 v59, -v57, v58, 1.0
	v_fmac_f32_e32 v58, v59, v58
	v_div_scale_f32 v59, vcc, v56, v54, v56
	v_mul_f32_e32 v60, v59, v58
	v_fma_f32 v61, -v57, v60, v59
	v_fmac_f32_e32 v60, v61, v58
	v_fma_f32 v57, -v57, v60, v59
	v_div_fmas_f32 v57, v57, v58, v60
	v_div_fixup_f32 v54, v57, v54, v56
	v_pk_mul_f32 v[52:53], v[54:55], v[52:53]
	v_lshlrev_b32_e32 v54, 16, v158
	v_cvt_pk_bf16_f32 v123, v52, v53
	s_nop 1
	v_permlane32_swap_b32_e32 v120, v122
	v_permlane32_swap_b32_e32 v121, v123
	global_store_dwordx4 v[148:149], v[120:123], off offset:32
	ds_read2st64_b32 v[50:51], v104 offset0:16 offset1:17
	v_and_b32_e32 v55, 0xffff0000, v158
	v_mul_f32_e32 v52, 0xbfb8aa3b, v54
	v_exp_f32_e32 v52, v52
	s_waitcnt lgkmcnt(0)
	v_pk_mul_f32 v[50:51], v[72:73], v[50:51] op_sel_hi:[0,1]
	v_pk_fma_f32 v[34:35], v[34:35], v[66:67], v[50:51] op_sel_hi:[1,0,1]
	v_mul_f32_e32 v50, 0xbfb8aa3b, v55
	v_exp_f32_e32 v53, v50
	v_pk_mul_f32 v[34:35], v[0:1], v[34:35] op_sel_hi:[0,1]
	v_pk_add_f32 v[50:51], v[52:53], 1.0 op_sel_hi:[1,0]
	s_nop 0
	v_rcp_f32_e32 v53, v51
	s_nop 0
	v_mul_f32_e32 v51, v55, v53
	v_rcp_f32_e32 v53, v50
	s_nop 0
	v_mul_f32_e32 v50, v54, v53
	v_pk_mul_f32 v[34:35], v[50:51], v[34:35]
	ds_read2st64_b32 v[50:51], v104 offset0:18 offset1:19
	v_lshlrev_b32_e32 v54, 16, v159
	v_and_b32_e32 v55, 0xffff0000, v159
	v_mul_f32_e32 v52, 0xbfb8aa3b, v54
	v_exp_f32_e32 v52, v52
	s_waitcnt lgkmcnt(0)
	v_pk_mul_f32 v[50:51], v[72:73], v[50:51] op_sel_hi:[0,1]
	v_pk_fma_f32 v[36:37], v[36:37], v[66:67], v[50:51] op_sel_hi:[1,0,1]
	v_mul_f32_e32 v50, 0xbfb8aa3b, v55
	v_exp_f32_e32 v53, v50
	v_pk_mul_f32 v[36:37], v[0:1], v[36:37] op_sel_hi:[0,1]
	v_cvt_pk_bf16_f32 v124, v34, v35
	v_pk_add_f32 v[50:51], v[52:53], 1.0 op_sel_hi:[1,0]
	s_nop 0
	v_rcp_f32_e32 v53, v51
	s_nop 0
	v_mul_f32_e32 v51, v55, v53
	v_rcp_f32_e32 v53, v50
	s_nop 0
	v_mul_f32_e32 v50, v54, v53
	v_pk_mul_f32 v[36:37], v[50:51], v[36:37]
	v_lshlrev_b32_e32 v50, 16, v160
	v_cvt_pk_bf16_f32 v125, v36, v37
	v_and_b32_e32 v51, 0xffff0000, v160
	ds_read2st64_b32 v[34:35], v104 offset0:20 offset1:21
	v_mul_f32_e32 v36, 0xbfb8aa3b, v50
	v_mul_f32_e32 v37, 0xbfb8aa3b, v51
	v_exp_f32_e32 v36, v36
	v_exp_f32_e32 v37, v37
	s_waitcnt lgkmcnt(0)
	v_pk_mul_f32 v[34:35], v[72:73], v[34:35] op_sel_hi:[0,1]
	v_pk_fma_f32 v[34:35], v[38:39], v[66:67], v[34:35] op_sel_hi:[1,0,1]
	v_pk_add_f32 v[36:37], v[36:37], 1.0 op_sel_hi:[1,0]
	s_nop 0
	v_div_scale_f32 v38, s[0:1], v37, v37, v51
	v_rcp_f32_e32 v39, v38
	v_pk_mul_f32 v[34:35], v[0:1], v[34:35] op_sel_hi:[0,1]
	v_fma_f32 v52, -v38, v39, 1.0
	v_fmac_f32_e32 v39, v52, v39
	v_div_scale_f32 v52, vcc, v51, v37, v51
	v_mul_f32_e32 v53, v52, v39
	v_fma_f32 v54, -v38, v53, v52
	v_fmac_f32_e32 v53, v54, v39
	v_fma_f32 v38, -v38, v53, v52
	v_div_fmas_f32 v38, v38, v39, v53
	v_div_fixup_f32 v37, v38, v37, v51
	v_rcp_f32_e32 v39, v36
	s_nop 0
	v_mul_f32_e32 v36, v50, v39
	v_lshlrev_b32_e32 v50, 16, v161
	v_and_b32_e32 v51, 0xffff0000, v161
	v_pk_mul_f32 v[34:35], v[36:37], v[34:35]
	ds_read2st64_b32 v[36:37], v104 offset0:22 offset1:23
	v_mul_f32_e32 v38, 0xbfb8aa3b, v50
	v_mul_f32_e32 v39, 0xbfb8aa3b, v51
	v_exp_f32_e32 v38, v38
	v_exp_f32_e32 v39, v39
	s_waitcnt lgkmcnt(0)
	v_pk_mul_f32 v[36:37], v[72:73], v[36:37] op_sel_hi:[0,1]
	v_pk_fma_f32 v[36:37], v[40:41], v[66:67], v[36:37] op_sel_hi:[1,0,1]
	v_cvt_pk_bf16_f32 v126, v34, v35
	v_pk_add_f32 v[38:39], v[38:39], 1.0 op_sel_hi:[1,0]
	v_pk_mul_f32 v[36:37], v[0:1], v[36:37] op_sel_hi:[0,1]
	v_rcp_f32_e32 v41, v39
	s_nop 0
	v_mul_f32_e32 v39, v51, v41
	v_rcp_f32_e32 v41, v38
	s_nop 0
	v_mul_f32_e32 v38, v50, v41
	v_pk_mul_f32 v[36:37], v[38:39], v[36:37]
	v_lshlrev_b32_e32 v38, 16, v162
	v_and_b32_e32 v39, 0xffff0000, v162
	v_cvt_pk_bf16_f32 v127, v36, v37
	v_mul_f32_e32 v36, 0xbfb8aa3b, v38
	v_mul_f32_e32 v37, 0xbfb8aa3b, v39
	v_exp_f32_e32 v36, v36
	v_exp_f32_e32 v37, v37
	s_nop 1
	v_permlane32_swap_b32_e32 v124, v126
	v_permlane32_swap_b32_e32 v125, v127
	global_store_dwordx4 v[148:149], v[124:127], off offset:64
	ds_read2st64_b32 v[34:35], v104 offset0:24 offset1:25
	v_pk_add_f32 v[36:37], v[36:37], 1.0 op_sel_hi:[1,0]
	s_nop 0
	v_div_scale_f32 v40, s[0:1], v37, v37, v39
	v_rcp_f32_e32 v41, v40
	s_waitcnt lgkmcnt(0)
; DI unsigned pk2(float lo, float hi) { f32x2 v = {lo, hi}; return __builtin_bit_cast(unsigned, __builtin_convertvector(v, bf2_t)); }
; DI float bflo(unsigned w) { return __uint_as_float(w << 16); }
; DI float bfhi(unsigned w) { return __uint_as_float(w & 0xffff0000u); }
; DI void attn_unit(const Params& p, int b, int h, int qb, LAS unsigned char* lds, int tid, int lane, int wave) {
;     ...
; #pragma unroll
;         for (int i = 0; i < 4; ++i)
; #pragma unroll
;             for (int q = 0; q < 4; ++q) {
;                 float gv[4] = {bflo(gw[i][q].x), bfhi(gw[i][q].x), bflo(gw[i][q].y), bfhi(gw[i][q].y)}; float ov[4];
; #pragma unroll
;                 for (int e = 0; e < 4; ++e) { const float val = (o[i][q * 4 + e] * a0 + MB[(i * 16 + q * 4 + e) * 64] * a1) * inv; ov[e] = val * (gv[e] / (1.f + __expf(-gv[e]))); }
;                 *(u32x2*)(op + i * 32 + q * 8) = (u32x2){pk2(ov[0], ov[1]), pk2(ov[2], ov[3])};
;             }
	v_pk_mul_f32 v[34:35], v[72:73], v[34:35] op_sel_hi:[0,1]
	v_pk_fma_f32 v[34:35], v[42:43], v[66:67], v[34:35] op_sel_hi:[1,0,1]
	v_fma_f32 v42, -v40, v41, 1.0
	v_fmac_f32_e32 v41, v42, v41
	v_div_scale_f32 v42, vcc, v39, v37, v39
	v_mul_f32_e32 v43, v42, v41
	v_fma_f32 v50, -v40, v43, v42
	v_fmac_f32_e32 v43, v50, v41
	v_fma_f32 v40, -v40, v43, v42
	v_div_fmas_f32 v40, v40, v41, v43
	v_div_fixup_f32 v37, v40, v37, v39
	v_div_scale_f32 v39, s[0:1], v36, v36, v38
	v_rcp_f32_e32 v40, v39
	v_pk_mul_f32 v[34:35], v[0:1], v[34:35] op_sel_hi:[0,1]
	v_fma_f32 v41, -v39, v40, 1.0
	v_fmac_f32_e32 v40, v41, v40
	v_div_scale_f32 v41, vcc, v38, v36, v38
	v_mul_f32_e32 v42, v41, v40
	v_fma_f32 v43, -v39, v42, v41
	v_fmac_f32_e32 v42, v43, v40
	v_fma_f32 v39, -v39, v42, v41
	v_div_fmas_f32 v39, v39, v40, v42
	v_lshlrev_b32_e32 v40, 16, v163
	v_and_b32_e32 v41, 0xffff0000, v163
	v_div_fixup_f32 v36, v39, v36, v38
	v_mul_f32_e32 v38, 0xbfb8aa3b, v40
	v_mul_f32_e32 v39, 0xbfb8aa3b, v41
	v_exp_f32_e32 v38, v38
	v_exp_f32_e32 v39, v39
	v_pk_mul_f32 v[34:35], v[36:37], v[34:35]
	ds_read2st64_b32 v[36:37], v104 offset0:26 offset1:27
	v_cvt_pk_bf16_f32 v128, v34, v35
	v_pk_add_f32 v[38:39], v[38:39], 1.0 op_sel_hi:[1,0]
	s_waitcnt lgkmcnt(0)
	v_pk_mul_f32 v[36:37], v[72:73], v[36:37] op_sel_hi:[0,1]
	v_div_scale_f32 v42, s[0:1], v39, v39, v41
	v_rcp_f32_e32 v43, v42
	v_pk_fma_f32 v[36:37], v[44:45], v[66:67], v[36:37] op_sel_hi:[1,0,1]
	v_fma_f32 v44, -v42, v43, 1.0
	v_fmac_f32_e32 v43, v44, v43
	v_div_scale_f32 v44, vcc, v41, v39, v41
	v_mul_f32_e32 v45, v44, v43
	v_fma_f32 v50, -v42, v45, v44
	v_fmac_f32_e32 v45, v50, v43
	v_fma_f32 v42, -v42, v45, v44
	v_div_fmas_f32 v42, v42, v43, v45
	v_div_fixup_f32 v39, v42, v39, v41
	v_div_scale_f32 v41, s[0:1], v38, v38, v40
	v_rcp_f32_e32 v42, v41
	v_pk_mul_f32 v[36:37], v[0:1], v[36:37] op_sel_hi:[0,1]
	v_fma_f32 v43, -v41, v42, 1.0
	v_fmac_f32_e32 v42, v43, v42
	v_div_scale_f32 v43, vcc, v40, v38, v40
	v_mul_f32_e32 v44, v43, v42
	v_fma_f32 v45, -v41, v44, v43
	v_fmac_f32_e32 v44, v45, v42
	v_fma_f32 v41, -v41, v44, v43
	v_div_fmas_f32 v41, v41, v42, v44
	v_div_fixup_f32 v38, v41, v38, v40
	v_pk_mul_f32 v[36:37], v[38:39], v[36:37]
	v_lshlrev_b32_e32 v38, 16, v164
	v_and_b32_e32 v39, 0xffff0000, v164
	v_cvt_pk_bf16_f32 v129, v36, v37
	v_mul_f32_e32 v36, 0xbfb8aa3b, v38
	v_mul_f32_e32 v37, 0xbfb8aa3b, v39
	v_exp_f32_e32 v36, v36
	v_exp_f32_e32 v37, v37
	ds_read2st64_b32 v[34:35], v104 offset0:28 offset1:29
	v_pk_add_f32 v[36:37], v[36:37], 1.0 op_sel_hi:[1,0]
	s_nop 0
	v_div_scale_f32 v40, s[0:1], v37, v37, v39
	v_rcp_f32_e32 v41, v40
	s_waitcnt lgkmcnt(0)
	v_pk_mul_f32 v[34:35], v[72:73], v[34:35] op_sel_hi:[0,1]
	v_pk_fma_f32 v[34:35], v[46:47], v[66:67], v[34:35] op_sel_hi:[1,0,1]
	v_fma_f32 v42, -v40, v41, 1.0
	v_fmac_f32_e32 v41, v42, v41
	v_div_scale_f32 v42, vcc, v39, v37, v39
	v_mul_f32_e32 v43, v42, v41
	v_fma_f32 v44, -v40, v43, v42
	v_fmac_f32_e32 v43, v44, v41
	v_fma_f32 v40, -v40, v43, v42
	v_div_fmas_f32 v40, v40, v41, v43
	v_div_fixup_f32 v37, v40, v37, v39
	v_div_scale_f32 v39, s[0:1], v36, v36, v38
	v_rcp_f32_e32 v40, v39
	v_pk_mul_f32 v[34:35], v[0:1], v[34:35] op_sel_hi:[0,1]
	v_fma_f32 v41, -v39, v40, 1.0
	v_fmac_f32_e32 v40, v41, v40
	v_div_scale_f32 v41, vcc, v38, v36, v38
	v_mul_f32_e32 v42, v41, v40
	v_fma_f32 v43, -v39, v42, v41
	v_fmac_f32_e32 v42, v43, v40
	v_fma_f32 v39, -v39, v42, v41
	v_div_fmas_f32 v39, v39, v40, v42
	v_lshlrev_b32_e32 v40, 16, v165
	v_and_b32_e32 v41, 0xffff0000, v165
	v_div_fixup_f32 v36, v39, v36, v38
	v_mul_f32_e32 v38, 0xbfb8aa3b, v40
	v_mul_f32_e32 v39, 0xbfb8aa3b, v41
	v_exp_f32_e32 v38, v38
	v_exp_f32_e32 v39, v39
	v_pk_mul_f32 v[34:35], v[36:37], v[34:35]
	ds_read2st64_b32 v[36:37], v104 offset0:30 offset1:31
	v_cvt_pk_bf16_f32 v130, v34, v35
	v_pk_add_f32 v[38:39], v[38:39], 1.0 op_sel_hi:[1,0]
	s_waitcnt lgkmcnt(0)
	v_pk_mul_f32 v[36:37], v[72:73], v[36:37] op_sel_hi:[0,1]
	v_div_scale_f32 v42, s[0:1], v39, v39, v41
	v_rcp_f32_e32 v43, v42
	v_pk_fma_f32 v[36:37], v[48:49], v[66:67], v[36:37] op_sel_hi:[1,0,1]
	v_fma_f32 v44, -v42, v43, 1.0
	v_fmac_f32_e32 v43, v44, v43
	v_div_scale_f32 v44, vcc, v41, v39, v41
	v_mul_f32_e32 v45, v44, v43
	v_fma_f32 v46, -v42, v45, v44
	v_fmac_f32_e32 v45, v46, v43
	v_fma_f32 v42, -v42, v45, v44
	v_div_fmas_f32 v42, v42, v43, v45
	v_div_fixup_f32 v39, v42, v39, v41
	v_div_scale_f32 v41, s[0:1], v38, v38, v40
	v_rcp_f32_e32 v42, v41
	v_pk_mul_f32 v[36:37], v[0:1], v[36:37] op_sel_hi:[0,1]
	v_fma_f32 v43, -v41, v42, 1.0
	v_fmac_f32_e32 v42, v43, v42
	v_div_scale_f32 v43, vcc, v40, v38, v40
	v_mul_f32_e32 v44, v43, v42
	v_fma_f32 v45, -v41, v44, v43
	v_fmac_f32_e32 v44, v45, v42
	v_fma_f32 v41, -v41, v44, v43
	v_div_fmas_f32 v41, v41, v42, v44
	v_div_fixup_f32 v38, v41, v38, v40
	v_pk_mul_f32 v[36:37], v[38:39], v[36:37]
	v_lshlrev_b32_e32 v38, 16, v166
	v_cvt_pk_bf16_f32 v131, v36, v37
	s_nop 1
	v_permlane32_swap_b32_e32 v128, v130
	v_permlane32_swap_b32_e32 v129, v131
	global_store_dwordx4 v[148:149], v[128:131], off offset:96
	ds_read2st64_b32 v[34:35], v104 offset0:32 offset1:33
	v_and_b32_e32 v39, 0xffff0000, v166
	v_mul_f32_e32 v36, 0xbfb8aa3b, v38
	v_exp_f32_e32 v36, v36
	s_waitcnt lgkmcnt(0)
	v_pk_mul_f32 v[34:35], v[72:73], v[34:35] op_sel_hi:[0,1]
	v_pk_fma_f32 v[18:19], v[18:19], v[66:67], v[34:35] op_sel_hi:[1,0,1]
	v_mul_f32_e32 v34, 0xbfb8aa3b, v39
	v_exp_f32_e32 v37, v34
	v_pk_mul_f32 v[18:19], v[0:1], v[18:19] op_sel_hi:[0,1]
	v_pk_add_f32 v[34:35], v[36:37], 1.0 op_sel_hi:[1,0]
	s_nop 0
	v_rcp_f32_e32 v37, v35
	s_nop 0
	v_mul_f32_e32 v35, v39, v37
	v_rcp_f32_e32 v37, v34
	s_nop 0
	v_mul_f32_e32 v34, v38, v37
	v_pk_mul_f32 v[18:19], v[34:35], v[18:19]
	ds_read2st64_b32 v[34:35], v104 offset0:34 offset1:35
	v_lshlrev_b32_e32 v38, 16, v167
	v_and_b32_e32 v39, 0xffff0000, v167
	v_mul_f32_e32 v36, 0xbfb8aa3b, v38
	v_exp_f32_e32 v36, v36
	s_waitcnt lgkmcnt(0)
; DI unsigned pk2(float lo, float hi) { f32x2 v = {lo, hi}; return __builtin_bit_cast(unsigned, __builtin_convertvector(v, bf2_t)); }
; DI float bflo(unsigned w) { return __uint_as_float(w << 16); }
; DI float bfhi(unsigned w) { return __uint_as_float(w & 0xffff0000u); }
; DI void attn_unit(const Params& p, int b, int h, int qb, LAS unsigned char* lds, int tid, int lane, int wave) {
;     ...
; #pragma unroll
;         for (int i = 0; i < 4; ++i)
; #pragma unroll
;             for (int q = 0; q < 4; ++q) {
;                 float gv[4] = {bflo(gw[i][q].x), bfhi(gw[i][q].x), bflo(gw[i][q].y), bfhi(gw[i][q].y)}; float ov[4];
; #pragma unroll
;                 for (int e = 0; e < 4; ++e) { const float val = (o[i][q * 4 + e] * a0 + MB[(i * 16 + q * 4 + e) * 64] * a1) * inv; ov[e] = val * (gv[e] / (1.f + __expf(-gv[e]))); }
;                 *(u32x2*)(op + i * 32 + q * 8) = (u32x2){pk2(ov[0], ov[1]), pk2(ov[2], ov[3])};
;             }
	v_pk_mul_f32 v[34:35], v[72:73], v[34:35] op_sel_hi:[0,1]
	v_pk_fma_f32 v[20:21], v[20:21], v[66:67], v[34:35] op_sel_hi:[1,0,1]
	v_mul_f32_e32 v34, 0xbfb8aa3b, v39
	v_exp_f32_e32 v37, v34
	v_pk_mul_f32 v[20:21], v[0:1], v[20:21] op_sel_hi:[0,1]
	v_cvt_pk_bf16_f32 v132, v18, v19
	v_pk_add_f32 v[34:35], v[36:37], 1.0 op_sel_hi:[1,0]
	s_nop 0
	v_rcp_f32_e32 v37, v35
	s_nop 0
	v_mul_f32_e32 v35, v39, v37
	v_rcp_f32_e32 v37, v34
	s_nop 0
	v_mul_f32_e32 v34, v38, v37
	v_pk_mul_f32 v[20:21], v[34:35], v[20:21]
	v_lshlrev_b32_e32 v34, 16, v168
	v_cvt_pk_bf16_f32 v133, v20, v21
	v_and_b32_e32 v35, 0xffff0000, v168
	ds_read2st64_b32 v[18:19], v104 offset0:36 offset1:37
	v_mul_f32_e32 v20, 0xbfb8aa3b, v34
	v_mul_f32_e32 v21, 0xbfb8aa3b, v35
	v_exp_f32_e32 v20, v20
	v_exp_f32_e32 v21, v21
	s_waitcnt lgkmcnt(0)
	v_pk_mul_f32 v[18:19], v[72:73], v[18:19] op_sel_hi:[0,1]
	v_pk_fma_f32 v[18:19], v[22:23], v[66:67], v[18:19] op_sel_hi:[1,0,1]
	v_pk_add_f32 v[20:21], v[20:21], 1.0 op_sel_hi:[1,0]
	s_nop 0
	v_div_scale_f32 v22, s[0:1], v21, v21, v35
	v_rcp_f32_e32 v23, v22
	v_pk_mul_f32 v[18:19], v[0:1], v[18:19] op_sel_hi:[0,1]
	v_fma_f32 v36, -v22, v23, 1.0
	v_fmac_f32_e32 v23, v36, v23
	v_div_scale_f32 v36, vcc, v35, v21, v35
	v_mul_f32_e32 v37, v36, v23
	v_fma_f32 v38, -v22, v37, v36
	v_fmac_f32_e32 v37, v38, v23
	v_fma_f32 v22, -v22, v37, v36
	v_div_fmas_f32 v22, v22, v23, v37
	v_div_fixup_f32 v21, v22, v21, v35
	v_rcp_f32_e32 v23, v20
	s_nop 0
	v_mul_f32_e32 v20, v34, v23
	v_lshlrev_b32_e32 v34, 16, v169
	v_and_b32_e32 v35, 0xffff0000, v169
	v_pk_mul_f32 v[18:19], v[20:21], v[18:19]
	ds_read2st64_b32 v[20:21], v104 offset0:38 offset1:39
	v_mul_f32_e32 v22, 0xbfb8aa3b, v34
	v_mul_f32_e32 v23, 0xbfb8aa3b, v35
	v_exp_f32_e32 v22, v22
	v_exp_f32_e32 v23, v23
	s_waitcnt lgkmcnt(0)
	v_pk_mul_f32 v[20:21], v[72:73], v[20:21] op_sel_hi:[0,1]
	v_pk_fma_f32 v[20:21], v[24:25], v[66:67], v[20:21] op_sel_hi:[1,0,1]
	v_cvt_pk_bf16_f32 v134, v18, v19
	v_pk_add_f32 v[22:23], v[22:23], 1.0 op_sel_hi:[1,0]
	v_pk_mul_f32 v[20:21], v[0:1], v[20:21] op_sel_hi:[0,1]
	v_rcp_f32_e32 v25, v23
	s_nop 0
	v_mul_f32_e32 v23, v35, v25
	v_rcp_f32_e32 v25, v22
	s_nop 0
	v_mul_f32_e32 v22, v34, v25
	v_pk_mul_f32 v[20:21], v[22:23], v[20:21]
	v_lshlrev_b32_e32 v22, 16, v170
	v_and_b32_e32 v23, 0xffff0000, v170
	v_cvt_pk_bf16_f32 v135, v20, v21
	v_mul_f32_e32 v20, 0xbfb8aa3b, v22
	v_mul_f32_e32 v21, 0xbfb8aa3b, v23
	v_exp_f32_e32 v20, v20
	v_exp_f32_e32 v21, v21
	s_nop 1
	v_permlane32_swap_b32_e32 v132, v134
	v_permlane32_swap_b32_e32 v133, v135
	global_store_dwordx4 v[148:149], v[132:135], off offset:128
	ds_read2st64_b32 v[18:19], v104 offset0:40 offset1:41
	v_pk_add_f32 v[20:21], v[20:21], 1.0 op_sel_hi:[1,0]
	s_nop 0
	v_div_scale_f32 v24, s[0:1], v21, v21, v23
	v_rcp_f32_e32 v25, v24
	s_waitcnt lgkmcnt(0)
	v_pk_mul_f32 v[18:19], v[72:73], v[18:19] op_sel_hi:[0,1]
	v_pk_fma_f32 v[18:19], v[26:27], v[66:67], v[18:19] op_sel_hi:[1,0,1]
	v_fma_f32 v26, -v24, v25, 1.0
	v_fmac_f32_e32 v25, v26, v25
	v_div_scale_f32 v26, vcc, v23, v21, v23
	v_mul_f32_e32 v27, v26, v25
	v_fma_f32 v34, -v24, v27, v26
	v_fmac_f32_e32 v27, v34, v25
	v_fma_f32 v24, -v24, v27, v26
	v_div_fmas_f32 v24, v24, v25, v27
	v_div_fixup_f32 v21, v24, v21, v23
	v_div_scale_f32 v23, s[0:1], v20, v20, v22
	v_rcp_f32_e32 v24, v23
	v_pk_mul_f32 v[18:19], v[0:1], v[18:19] op_sel_hi:[0,1]
	v_fma_f32 v25, -v23, v24, 1.0
	v_fmac_f32_e32 v24, v25, v24
	v_div_scale_f32 v25, vcc, v22, v20, v22
	v_mul_f32_e32 v26, v25, v24
	v_fma_f32 v27, -v23, v26, v25
	v_fmac_f32_e32 v26, v27, v24
	v_fma_f32 v23, -v23, v26, v25
	v_div_fmas_f32 v23, v23, v24, v26
	v_lshlrev_b32_e32 v24, 16, v171
	v_and_b32_e32 v25, 0xffff0000, v171
	v_div_fixup_f32 v20, v23, v20, v22
	v_mul_f32_e32 v22, 0xbfb8aa3b, v24
	v_mul_f32_e32 v23, 0xbfb8aa3b, v25
	v_exp_f32_e32 v22, v22
	v_exp_f32_e32 v23, v23
	v_pk_mul_f32 v[18:19], v[20:21], v[18:19]
	ds_read2st64_b32 v[20:21], v104 offset0:42 offset1:43
	v_cvt_pk_bf16_f32 v136, v18, v19
	v_pk_add_f32 v[22:23], v[22:23], 1.0 op_sel_hi:[1,0]
	s_waitcnt lgkmcnt(0)
	v_pk_mul_f32 v[20:21], v[72:73], v[20:21] op_sel_hi:[0,1]
	v_div_scale_f32 v26, s[0:1], v23, v23, v25
	v_rcp_f32_e32 v27, v26
	v_pk_fma_f32 v[20:21], v[28:29], v[66:67], v[20:21] op_sel_hi:[1,0,1]
	v_fma_f32 v28, -v26, v27, 1.0
	v_fmac_f32_e32 v27, v28, v27
	v_div_scale_f32 v28, vcc, v25, v23, v25
	v_mul_f32_e32 v29, v28, v27
	v_fma_f32 v34, -v26, v29, v28
	v_fmac_f32_e32 v29, v34, v27
	v_fma_f32 v26, -v26, v29, v28
	v_div_fmas_f32 v26, v26, v27, v29
	v_div_fixup_f32 v23, v26, v23, v25
	v_div_scale_f32 v25, s[0:1], v22, v22, v24
	v_rcp_f32_e32 v26, v25
	v_pk_mul_f32 v[20:21], v[0:1], v[20:21] op_sel_hi:[0,1]
	v_fma_f32 v27, -v25, v26, 1.0
	v_fmac_f32_e32 v26, v27, v26
	v_div_scale_f32 v27, vcc, v24, v22, v24
	v_mul_f32_e32 v28, v27, v26
	v_fma_f32 v29, -v25, v28, v27
	v_fmac_f32_e32 v28, v29, v26
	v_fma_f32 v25, -v25, v28, v27
	v_div_fmas_f32 v25, v25, v26, v28
	v_div_fixup_f32 v22, v25, v22, v24
	v_pk_mul_f32 v[20:21], v[22:23], v[20:21]
	v_lshlrev_b32_e32 v22, 16, v172
	v_and_b32_e32 v23, 0xffff0000, v172
	v_cvt_pk_bf16_f32 v137, v20, v21
	v_mul_f32_e32 v20, 0xbfb8aa3b, v22
	v_mul_f32_e32 v21, 0xbfb8aa3b, v23
	v_exp_f32_e32 v20, v20
	v_exp_f32_e32 v21, v21
	ds_read2st64_b32 v[18:19], v104 offset0:44 offset1:45
	v_pk_add_f32 v[20:21], v[20:21], 1.0 op_sel_hi:[1,0]
	s_nop 0
	v_div_scale_f32 v24, s[0:1], v21, v21, v23
	v_rcp_f32_e32 v25, v24
	s_waitcnt lgkmcnt(0)
; DI unsigned pk2(float lo, float hi) { f32x2 v = {lo, hi}; return __builtin_bit_cast(unsigned, __builtin_convertvector(v, bf2_t)); }
; DI float bflo(unsigned w) { return __uint_as_float(w << 16); }
; DI float bfhi(unsigned w) { return __uint_as_float(w & 0xffff0000u); }
; DI void attn_unit(const Params& p, int b, int h, int qb, LAS unsigned char* lds, int tid, int lane, int wave) {
;     ...
; #pragma unroll
;         for (int i = 0; i < 4; ++i)
; #pragma unroll
;             for (int q = 0; q < 4; ++q) {
;                 float gv[4] = {bflo(gw[i][q].x), bfhi(gw[i][q].x), bflo(gw[i][q].y), bfhi(gw[i][q].y)}; float ov[4];
; #pragma unroll
;                 for (int e = 0; e < 4; ++e) { const float val = (o[i][q * 4 + e] * a0 + MB[(i * 16 + q * 4 + e) * 64] * a1) * inv; ov[e] = val * (gv[e] / (1.f + __expf(-gv[e]))); }
;                 *(u32x2*)(op + i * 32 + q * 8) = (u32x2){pk2(ov[0], ov[1]), pk2(ov[2], ov[3])};
;             }
	v_pk_mul_f32 v[18:19], v[72:73], v[18:19] op_sel_hi:[0,1]
	v_pk_fma_f32 v[18:19], v[30:31], v[66:67], v[18:19] op_sel_hi:[1,0,1]
	v_fma_f32 v26, -v24, v25, 1.0
	v_fmac_f32_e32 v25, v26, v25
	v_div_scale_f32 v26, vcc, v23, v21, v23
	v_mul_f32_e32 v27, v26, v25
	v_fma_f32 v28, -v24, v27, v26
	v_fmac_f32_e32 v27, v28, v25
	v_fma_f32 v24, -v24, v27, v26
	v_div_fmas_f32 v24, v24, v25, v27
	v_div_fixup_f32 v21, v24, v21, v23
	v_div_scale_f32 v23, s[0:1], v20, v20, v22
	v_rcp_f32_e32 v24, v23
	v_pk_mul_f32 v[18:19], v[0:1], v[18:19] op_sel_hi:[0,1]
	v_fma_f32 v25, -v23, v24, 1.0
	v_fmac_f32_e32 v24, v25, v24
	v_div_scale_f32 v25, vcc, v22, v20, v22
	v_mul_f32_e32 v26, v25, v24
	v_fma_f32 v27, -v23, v26, v25
	v_fmac_f32_e32 v26, v27, v24
	v_fma_f32 v23, -v23, v26, v25
	v_div_fmas_f32 v23, v23, v24, v26
	v_lshlrev_b32_e32 v24, 16, v173
	v_and_b32_e32 v25, 0xffff0000, v173
	v_div_fixup_f32 v20, v23, v20, v22
	v_mul_f32_e32 v22, 0xbfb8aa3b, v24
	v_mul_f32_e32 v23, 0xbfb8aa3b, v25
	v_exp_f32_e32 v22, v22
	v_exp_f32_e32 v23, v23
	v_pk_mul_f32 v[18:19], v[20:21], v[18:19]
	ds_read2st64_b32 v[20:21], v104 offset0:46 offset1:47
	v_cvt_pk_bf16_f32 v138, v18, v19
	v_pk_add_f32 v[22:23], v[22:23], 1.0 op_sel_hi:[1,0]
	s_waitcnt lgkmcnt(0)
	v_pk_mul_f32 v[20:21], v[72:73], v[20:21] op_sel_hi:[0,1]
	v_div_scale_f32 v26, s[0:1], v23, v23, v25
	v_rcp_f32_e32 v27, v26
	v_pk_fma_f32 v[20:21], v[32:33], v[66:67], v[20:21] op_sel_hi:[1,0,1]
	v_fma_f32 v28, -v26, v27, 1.0
	v_fmac_f32_e32 v27, v28, v27
	v_div_scale_f32 v28, vcc, v25, v23, v25
	v_mul_f32_e32 v29, v28, v27
	v_fma_f32 v30, -v26, v29, v28
	v_fmac_f32_e32 v29, v30, v27
	v_fma_f32 v26, -v26, v29, v28
	v_div_fmas_f32 v26, v26, v27, v29
	v_div_fixup_f32 v23, v26, v23, v25
	v_div_scale_f32 v25, s[0:1], v22, v22, v24
	v_rcp_f32_e32 v26, v25
	v_pk_mul_f32 v[20:21], v[0:1], v[20:21] op_sel_hi:[0,1]
	v_fma_f32 v27, -v25, v26, 1.0
	v_fmac_f32_e32 v26, v27, v26
	v_div_scale_f32 v27, vcc, v24, v22, v24
	v_mul_f32_e32 v28, v27, v26
	v_fma_f32 v29, -v25, v28, v27
	v_fmac_f32_e32 v28, v29, v26
	v_fma_f32 v25, -v25, v28, v27
	v_div_fmas_f32 v25, v25, v26, v28
	v_div_fixup_f32 v22, v25, v22, v24
	v_pk_mul_f32 v[20:21], v[22:23], v[20:21]
	v_lshlrev_b32_e32 v22, 16, v174
	v_cvt_pk_bf16_f32 v139, v20, v21
	s_nop 1
	v_permlane32_swap_b32_e32 v136, v138
	v_permlane32_swap_b32_e32 v137, v139
	global_store_dwordx4 v[148:149], v[136:139], off offset:160
	ds_read2st64_b32 v[18:19], v104 offset0:48 offset1:49
	v_and_b32_e32 v23, 0xffff0000, v174
	v_mul_f32_e32 v20, 0xbfb8aa3b, v22
	v_exp_f32_e32 v20, v20
	s_waitcnt lgkmcnt(0)
	v_pk_mul_f32 v[18:19], v[72:73], v[18:19] op_sel_hi:[0,1]
	v_pk_fma_f32 v[2:3], v[2:3], v[66:67], v[18:19] op_sel_hi:[1,0,1]
	v_mul_f32_e32 v18, 0xbfb8aa3b, v23
	v_exp_f32_e32 v21, v18
	v_pk_mul_f32 v[2:3], v[0:1], v[2:3] op_sel_hi:[0,1]
	v_pk_add_f32 v[18:19], v[20:21], 1.0 op_sel_hi:[1,0]
	s_nop 0
	v_rcp_f32_e32 v21, v19
	s_nop 0
	v_mul_f32_e32 v19, v23, v21
	v_rcp_f32_e32 v21, v18
	s_nop 0
	v_mul_f32_e32 v18, v22, v21
	v_pk_mul_f32 v[2:3], v[18:19], v[2:3]
	ds_read2st64_b32 v[18:19], v104 offset0:50 offset1:51
	v_lshlrev_b32_e32 v22, 16, v175
	v_and_b32_e32 v23, 0xffff0000, v175
	v_mul_f32_e32 v20, 0xbfb8aa3b, v22
	v_exp_f32_e32 v20, v20
	s_waitcnt lgkmcnt(0)
	v_pk_mul_f32 v[18:19], v[72:73], v[18:19] op_sel_hi:[0,1]
	v_pk_fma_f32 v[4:5], v[4:5], v[66:67], v[18:19] op_sel_hi:[1,0,1]
	v_mul_f32_e32 v18, 0xbfb8aa3b, v23
	v_exp_f32_e32 v21, v18
	v_pk_mul_f32 v[4:5], v[0:1], v[4:5] op_sel_hi:[0,1]
	v_cvt_pk_bf16_f32 v140, v2, v3
	v_pk_add_f32 v[18:19], v[20:21], 1.0 op_sel_hi:[1,0]
	s_nop 0
	v_rcp_f32_e32 v21, v19
	s_nop 0
	v_mul_f32_e32 v19, v23, v21
	v_rcp_f32_e32 v21, v18
	s_nop 0
	v_mul_f32_e32 v18, v22, v21
	v_pk_mul_f32 v[4:5], v[18:19], v[4:5]
	v_lshlrev_b32_e32 v18, 16, v176
	v_cvt_pk_bf16_f32 v141, v4, v5
	v_and_b32_e32 v19, 0xffff0000, v176
	ds_read2st64_b32 v[2:3], v104 offset0:52 offset1:53
	v_mul_f32_e32 v4, 0xbfb8aa3b, v18
	v_mul_f32_e32 v5, 0xbfb8aa3b, v19
	v_exp_f32_e32 v4, v4
	v_exp_f32_e32 v5, v5
	s_waitcnt lgkmcnt(0)
	v_pk_mul_f32 v[2:3], v[72:73], v[2:3] op_sel_hi:[0,1]
	v_pk_fma_f32 v[2:3], v[6:7], v[66:67], v[2:3] op_sel_hi:[1,0,1]
	v_pk_add_f32 v[4:5], v[4:5], 1.0 op_sel_hi:[1,0]
	s_nop 0
	v_div_scale_f32 v6, s[0:1], v5, v5, v19
	v_rcp_f32_e32 v7, v6
	v_pk_mul_f32 v[2:3], v[0:1], v[2:3] op_sel_hi:[0,1]
	v_fma_f32 v20, -v6, v7, 1.0
	v_fmac_f32_e32 v7, v20, v7
	v_div_scale_f32 v20, vcc, v19, v5, v19
	v_mul_f32_e32 v21, v20, v7
	v_fma_f32 v22, -v6, v21, v20
	v_fmac_f32_e32 v21, v22, v7
	v_fma_f32 v6, -v6, v21, v20
	v_div_fmas_f32 v6, v6, v7, v21
	v_div_fixup_f32 v5, v6, v5, v19
	v_rcp_f32_e32 v7, v4
	s_nop 0
	v_mul_f32_e32 v4, v18, v7
	v_lshlrev_b32_e32 v18, 16, v177
	v_and_b32_e32 v19, 0xffff0000, v177
	v_pk_mul_f32 v[2:3], v[4:5], v[2:3]
	ds_read2st64_b32 v[4:5], v104 offset0:54 offset1:55
	v_mul_f32_e32 v6, 0xbfb8aa3b, v18
	v_mul_f32_e32 v7, 0xbfb8aa3b, v19
	v_exp_f32_e32 v6, v6
	v_exp_f32_e32 v7, v7
	s_waitcnt lgkmcnt(0)
; DI unsigned pk2(float lo, float hi) { f32x2 v = {lo, hi}; return __builtin_bit_cast(unsigned, __builtin_convertvector(v, bf2_t)); }
; DI float bflo(unsigned w) { return __uint_as_float(w << 16); }
; DI float bfhi(unsigned w) { return __uint_as_float(w & 0xffff0000u); }
; DI void attn_unit(const Params& p, int b, int h, int qb, LAS unsigned char* lds, int tid, int lane, int wave) {
;     ...
; #pragma unroll
;         for (int i = 0; i < 4; ++i)
; #pragma unroll
;             for (int q = 0; q < 4; ++q) {
;                 float gv[4] = {bflo(gw[i][q].x), bfhi(gw[i][q].x), bflo(gw[i][q].y), bfhi(gw[i][q].y)}; float ov[4];
; #pragma unroll
;                 for (int e = 0; e < 4; ++e) { const float val = (o[i][q * 4 + e] * a0 + MB[(i * 16 + q * 4 + e) * 64] * a1) * inv; ov[e] = val * (gv[e] / (1.f + __expf(-gv[e]))); }
;                 *(u32x2*)(op + i * 32 + q * 8) = (u32x2){pk2(ov[0], ov[1]), pk2(ov[2], ov[3])};
;             }
	v_pk_mul_f32 v[4:5], v[72:73], v[4:5] op_sel_hi:[0,1]
	v_pk_fma_f32 v[4:5], v[8:9], v[66:67], v[4:5] op_sel_hi:[1,0,1]
	v_cvt_pk_bf16_f32 v142, v2, v3
	v_pk_add_f32 v[6:7], v[6:7], 1.0 op_sel_hi:[1,0]
	v_pk_mul_f32 v[4:5], v[0:1], v[4:5] op_sel_hi:[0,1]
	v_rcp_f32_e32 v9, v7
	s_nop 0
	v_mul_f32_e32 v7, v19, v9
	v_rcp_f32_e32 v9, v6
	s_nop 0
	v_mul_f32_e32 v6, v18, v9
	v_pk_mul_f32 v[4:5], v[6:7], v[4:5]
	v_lshlrev_b32_e32 v6, 16, v178
	v_and_b32_e32 v7, 0xffff0000, v178
	v_cvt_pk_bf16_f32 v143, v4, v5
	v_mul_f32_e32 v4, 0xbfb8aa3b, v6
	v_mul_f32_e32 v5, 0xbfb8aa3b, v7
	v_exp_f32_e32 v4, v4
	v_exp_f32_e32 v5, v5
	s_nop 1
	v_permlane32_swap_b32_e32 v140, v142
	v_permlane32_swap_b32_e32 v141, v143
	global_store_dwordx4 v[148:149], v[140:143], off offset:192
	ds_read2st64_b32 v[2:3], v104 offset0:56 offset1:57
	v_pk_add_f32 v[4:5], v[4:5], 1.0 op_sel_hi:[1,0]
	s_nop 0
	v_div_scale_f32 v8, s[0:1], v5, v5, v7
	v_rcp_f32_e32 v9, v8
	s_waitcnt lgkmcnt(0)
	v_pk_mul_f32 v[2:3], v[72:73], v[2:3] op_sel_hi:[0,1]
	v_pk_fma_f32 v[2:3], v[10:11], v[66:67], v[2:3] op_sel_hi:[1,0,1]
	v_fma_f32 v10, -v8, v9, 1.0
	v_fmac_f32_e32 v9, v10, v9
	v_div_scale_f32 v10, vcc, v7, v5, v7
	v_mul_f32_e32 v11, v10, v9
	v_fma_f32 v18, -v8, v11, v10
	v_fmac_f32_e32 v11, v18, v9
	v_fma_f32 v8, -v8, v11, v10
	v_div_fmas_f32 v8, v8, v9, v11
	v_div_fixup_f32 v5, v8, v5, v7
	v_div_scale_f32 v7, s[0:1], v4, v4, v6
	v_rcp_f32_e32 v8, v7
	v_pk_mul_f32 v[2:3], v[0:1], v[2:3] op_sel_hi:[0,1]
	v_fma_f32 v9, -v7, v8, 1.0
	v_fmac_f32_e32 v8, v9, v8
	v_div_scale_f32 v9, vcc, v6, v4, v6
	v_mul_f32_e32 v10, v9, v8
	v_fma_f32 v11, -v7, v10, v9
	v_fmac_f32_e32 v10, v11, v8
	v_fma_f32 v7, -v7, v10, v9
	v_div_fmas_f32 v7, v7, v8, v10
	v_lshlrev_b32_e32 v8, 16, v179
	v_and_b32_e32 v9, 0xffff0000, v179
	v_div_fixup_f32 v4, v7, v4, v6
	v_mul_f32_e32 v6, 0xbfb8aa3b, v8
	v_mul_f32_e32 v7, 0xbfb8aa3b, v9
	v_exp_f32_e32 v6, v6
	v_exp_f32_e32 v7, v7
	v_pk_mul_f32 v[2:3], v[4:5], v[2:3]
	ds_read2st64_b32 v[4:5], v104 offset0:58 offset1:59
	v_cvt_pk_bf16_f32 v144, v2, v3
	v_pk_add_f32 v[6:7], v[6:7], 1.0 op_sel_hi:[1,0]
	s_waitcnt lgkmcnt(0)
	v_pk_mul_f32 v[4:5], v[72:73], v[4:5] op_sel_hi:[0,1]
	v_div_scale_f32 v10, s[0:1], v7, v7, v9
	v_rcp_f32_e32 v11, v10
	v_pk_fma_f32 v[4:5], v[12:13], v[66:67], v[4:5] op_sel_hi:[1,0,1]
	v_fma_f32 v12, -v10, v11, 1.0
	v_fmac_f32_e32 v11, v12, v11
	v_div_scale_f32 v12, vcc, v9, v7, v9
	v_mul_f32_e32 v13, v12, v11
	v_fma_f32 v18, -v10, v13, v12
	v_fmac_f32_e32 v13, v18, v11
	v_fma_f32 v10, -v10, v13, v12
	v_div_fmas_f32 v10, v10, v11, v13
	v_div_fixup_f32 v7, v10, v7, v9
	v_div_scale_f32 v9, s[0:1], v6, v6, v8
	v_rcp_f32_e32 v10, v9
	v_pk_mul_f32 v[4:5], v[0:1], v[4:5] op_sel_hi:[0,1]
	v_fma_f32 v11, -v9, v10, 1.0
	v_fmac_f32_e32 v10, v11, v10
	v_div_scale_f32 v11, vcc, v8, v6, v8
	v_mul_f32_e32 v12, v11, v10
	v_fma_f32 v13, -v9, v12, v11
	v_fmac_f32_e32 v12, v13, v10
	v_fma_f32 v9, -v9, v12, v11
	v_div_fmas_f32 v9, v9, v10, v12
	v_div_fixup_f32 v6, v9, v6, v8
	v_pk_mul_f32 v[4:5], v[6:7], v[4:5]
	v_lshlrev_b32_e32 v6, 16, v180
	v_and_b32_e32 v7, 0xffff0000, v180
	v_cvt_pk_bf16_f32 v145, v4, v5
	v_mul_f32_e32 v4, 0xbfb8aa3b, v6
	v_mul_f32_e32 v5, 0xbfb8aa3b, v7
	v_exp_f32_e32 v4, v4
	v_exp_f32_e32 v5, v5
	ds_read2st64_b32 v[2:3], v104 offset0:60 offset1:61
	v_pk_add_f32 v[4:5], v[4:5], 1.0 op_sel_hi:[1,0]
	s_nop 0
	v_div_scale_f32 v8, s[0:1], v5, v5, v7
	v_rcp_f32_e32 v9, v8
	s_waitcnt lgkmcnt(0)
	v_pk_mul_f32 v[2:3], v[72:73], v[2:3] op_sel_hi:[0,1]
	v_pk_fma_f32 v[2:3], v[14:15], v[66:67], v[2:3] op_sel_hi:[1,0,1]
	v_fma_f32 v10, -v8, v9, 1.0
	v_fmac_f32_e32 v9, v10, v9
	v_div_scale_f32 v10, vcc, v7, v5, v7
	v_mul_f32_e32 v11, v10, v9
	v_fma_f32 v12, -v8, v11, v10
	v_fmac_f32_e32 v11, v12, v9
	v_fma_f32 v8, -v8, v11, v10
	v_div_fmas_f32 v8, v8, v9, v11
	v_div_fixup_f32 v5, v8, v5, v7
	v_div_scale_f32 v7, s[0:1], v4, v4, v6
	v_rcp_f32_e32 v8, v7
	v_pk_mul_f32 v[2:3], v[0:1], v[2:3] op_sel_hi:[0,1]
	v_fma_f32 v9, -v7, v8, 1.0
	v_fmac_f32_e32 v8, v9, v8
	v_div_scale_f32 v9, vcc, v6, v4, v6
	v_mul_f32_e32 v10, v9, v8
	v_fma_f32 v11, -v7, v10, v9
	v_fmac_f32_e32 v10, v11, v8
	v_fma_f32 v7, -v7, v10, v9
	v_div_fmas_f32 v7, v7, v8, v10
	v_div_fixup_f32 v4, v7, v4, v6
	v_pk_mul_f32 v[2:3], v[4:5], v[2:3]
	ds_read2st64_b32 v[4:5], v104 offset0:62 offset1:63
	v_lshlrev_b32_e32 v8, 16, v181
	v_and_b32_e32 v9, 0xffff0000, v181
	v_mul_f32_e32 v6, 0xbfb8aa3b, v8
	v_exp_f32_e32 v6, v6
	s_waitcnt lgkmcnt(0)
	v_pk_mul_f32 v[4:5], v[72:73], v[4:5] op_sel_hi:[0,1]
	v_pk_fma_f32 v[4:5], v[16:17], v[66:67], v[4:5] op_sel_hi:[1,0,1]
	v_cvt_pk_bf16_f32 v146, v2, v3
	v_pk_mul_f32 v[4:5], v[0:1], v[4:5] op_sel_hi:[0,1]
	v_mul_f32_e32 v0, 0xbfb8aa3b, v9
	v_exp_f32_e32 v7, v0
	s_nop 0
	v_pk_add_f32 v[6:7], v[6:7], 1.0 op_sel_hi:[1,0]
	s_nop 0
	v_rcp_f32_e32 v10, v7
	s_nop 0
	v_mul_f32_e32 v7, v9, v10
	v_rcp_f32_e32 v9, v6
	s_nop 0
	v_mul_f32_e32 v6, v8, v9
	v_pk_mul_f32 v[4:5], v[6:7], v[4:5]
	s_nop 0
	v_cvt_pk_bf16_f32 v147, v4, v5
	s_nop 1
	v_permlane32_swap_b32_e32 v144, v146
	v_permlane32_swap_b32_e32 v145, v147
	global_store_dwordx4 v[148:149], v[144:147], off offset:224

; DI unsigned pk2(float lo, float hi) { f32x2 v = {lo, hi}; return __builtin_bit_cast(unsigned, __builtin_convertvector(v, bf2_t)); }
; DI float bflo(unsigned w) { return __uint_as_float(w << 16); }
; DI float bfhi(unsigned w) { return __uint_as_float(w & 0xffff0000u); }
; DI void attn_unit(const Params& p, int b, int h, int qb, LAS unsigned char* lds, int tid, int lane, int wave) {
;     ...
;     if (g == 0) {
;         const float m1 = MB[64 * 64], l1 = MB[65 * 64];
;         const float m = fmaxf(mrow, m1);
;         const float a0 = __builtin_amdgcn_exp2f(mrow - m), a1 = __builtin_amdgcn_exp2f(m1 - m);
;         const float inv = 1.0f / (lrow * a0 + l1 * a1);
;         const size_t tok = tokb + qr0 + r;
;         const bf16_t* gp = Z + tok * ZLD + Z_MG + h * 128 + 4 * hh;
;         bf16_t* op = OB + tok * DM + 512 + h * 128 + 4 * hh;
;         u32x2 gw[4][4];
; #pragma unroll
;         for (int i = 0; i < 4; ++i)
; #pragma unroll
;             for (int q = 0; q < 4; ++q) gw[i][q] = *(const u32x2*)(gp + i * 32 + q * 8);
; #pragma unroll
;         for (int i = 0; i < 4; ++i)
; #pragma unroll
;             for (int q = 0; q < 4; ++q) {
;                 float gv[4] = {bflo(gw[i][q].x), bfhi(gw[i][q].x), bflo(gw[i][q].y), bfhi(gw[i][q].y)}; float ov[4];
; #pragma unroll
;                 for (int e = 0; e < 4; ++e) { const float val = (o[i][q * 4 + e] * a0 + MB[(i * 16 + q * 4 + e) * 64] * a1) * inv; ov[e] = val * (gv[e] / (1.f + __expf(-gv[e]))); }
;                 *(u32x2*)(op + i * 32 + q * 8) = (u32x2){pk2(ov[0], ov[1]), pk2(ov[2], ov[3])};
;             }
.LBB0_460:
	s_cmp_gt_u32 s3, 3
	s_waitcnt lgkmcnt(0)
	s_barrier
	s_cbranch_scc1 .LBB0_425
	ds_read2st64_b32 v[70:71], v104 offset0:64 offset1:65
	v_max_f32_e32 v0, v204, v204
	s_lshl_b32 s92, s2, 8
	v_ashrrev_i32_e32 v183, 31, v182
	v_lshlrev_b64 v[102:103], 1, v[182:183]
	s_waitcnt lgkmcnt(0)
	v_max_f32_e32 v66, v70, v70
	v_max_f32_e32 v0, v0, v66
	v_sub_f32_e32 v66, v204, v0
	v_sub_f32_e32 v0, v70, v0
	v_exp_f32_e32 v66, v66
	v_exp_f32_e32 v67, v0
	v_mov_b32_e32 v69, v71
	v_lshlrev_b32_e32 v0, 12, v202
	s_mov_b64 s[0:1], 0x4600c00
	v_pk_mul_f32 v[68:69], v[68:69], v[66:67]
	s_nop 0
	v_add_f32_e32 v105, v68, v69
	v_lshl_add_u64 v[68:69], s[50:51], 0, v[0:1]
	v_lshl_add_u64 v[70:71], v[68:69], 0, s[92:93]
	v_lshlrev_b32_e32 v0, 11, v202
	v_lshl_add_u64 v[70:71], v[70:71], 0, v[102:103]
	v_sub_co_u32_e32 v72, vcc, 0, v0
	v_lshl_add_u64 v[106:107], v[70:71], 0, s[0:1]
	s_nop 0
	v_subb_co_u32_e64 v73, s[0:1], 0, 0, vcc
	s_mov_b32 s0, 0x4600000
	s_nop 0
	v_add_co_u32_e32 v70, vcc, s0, v70
	v_lshl_add_u64 v[68:69], v[68:69], 0, v[72:73]
	s_nop 0
	v_addc_co_u32_e32 v71, vcc, 0, v71, vcc
	v_div_scale_f32 v0, s[0:1], v105, v105, 1.0
	v_rcp_f32_e32 v106, v0
	v_lshl_add_u64 v[68:69], v[68:69], 0, s[92:93]
	v_lshl_add_u64 v[102:103], v[68:69], 0, v[102:103]
	s_mov_b64 s[0:1], 0xae00400
	v_fma_f32 v107, -v0, v106, 1.0
	v_fmac_f32_e32 v106, v107, v106
	v_div_scale_f32 v107, vcc, 1.0, v105, 1.0
	v_mul_f32_e32 v108, v107, v106
	v_fma_f32 v109, -v0, v108, v107
	v_fmac_f32_e32 v108, v109, v106
	v_fma_f32 v0, -v0, v108, v107
	v_div_fmas_f32 v0, v0, v106, v108
	ds_read2st64_b32 v[106:107], v104 offset1:1
	v_div_fixup_f32 v0, v0, v105, 1.0
	v_lshl_add_u64 v[68:69], v[102:103], 0, s[0:1]
	s_waitcnt vmcnt(0)
	v_lshlrev_b32_e32 v105, 16, v114
	v_and_b32_e32 v110, 0xffff0000, v114
	v_mul_f32_e32 v72, 0xbfb8aa3b, v105
	v_exp_f32_e32 v108, v72
	v_mov_b32_e32 v72, v67
	s_waitcnt lgkmcnt(0)
	v_pk_mul_f32 v[106:107], v[72:73], v[106:107] op_sel_hi:[0,1]
	v_pk_fma_f32 v[50:51], v[50:51], v[66:67], v[106:107] op_sel_hi:[1,0,1]
	v_mul_f32_e32 v67, 0xbfb8aa3b, v110
	v_exp_f32_e32 v109, v67
	v_pk_mul_f32 v[50:51], v[0:1], v[50:51] op_sel_hi:[0,1]
	v_pk_add_f32 v[106:107], v[108:109], 1.0 op_sel_hi:[1,0]
	s_nop 0
	v_rcp_f32_e32 v108, v107
	s_nop 0
	v_mul_f32_e32 v107, v110, v108
	v_rcp_f32_e32 v108, v106
	s_nop 0
	v_mul_f32_e32 v106, v105, v108
	v_lshlrev_b32_e32 v67, 16, v115
	v_pk_mul_f32 v[50:51], v[106:107], v[50:51]
	ds_read2st64_b32 v[106:107], v104 offset0:2 offset1:3
	v_and_b32_e32 v73, 0xffff0000, v115
	v_mul_f32_e32 v105, 0xbfb8aa3b, v67
	v_exp_f32_e32 v108, v105
	v_mul_f32_e32 v105, 0xbfb8aa3b, v73
	v_exp_f32_e32 v109, v105
	s_waitcnt lgkmcnt(0)
	v_pk_mul_f32 v[106:107], v[72:73], v[106:107] op_sel_hi:[0,1]
	v_pk_fma_f32 v[52:53], v[52:53], v[66:67], v[106:107] op_sel_hi:[1,0,1]
	v_cvt_pk_bf16_f32 v116, v50, v51
	v_pk_add_f32 v[106:107], v[108:109], 1.0 op_sel_hi:[1,0]
	v_pk_mul_f32 v[52:53], v[0:1], v[52:53] op_sel_hi:[0,1]
	v_rcp_f32_e32 v108, v107
	s_nop 0
	v_mul_f32_e32 v107, v73, v108
	v_div_scale_f32 v73, s[0:1], v106, v106, v67
	v_rcp_f32_e32 v105, v73
	s_mov_b32 s0, 0xae00000
	v_fma_f32 v108, -v73, v105, 1.0
	v_fmac_f32_e32 v105, v108, v105
	v_div_scale_f32 v108, vcc, v67, v106, v67
	v_mul_f32_e32 v109, v108, v105
	v_fma_f32 v110, -v73, v109, v108
	v_fmac_f32_e32 v109, v110, v105
	v_fma_f32 v73, -v73, v109, v108
	v_div_fmas_f32 v73, v73, v105, v109
	v_div_fixup_f32 v106, v73, v106, v67
	v_pk_mul_f32 v[52:53], v[106:107], v[52:53]
	v_lshlrev_b32_e32 v67, 16, v152
	v_cvt_pk_bf16_f32 v117, v52, v53
	v_add_co_u32_e32 v52, vcc, s0, v102
	v_and_b32_e32 v73, 0xffff0000, v152
	s_nop 0
	v_addc_co_u32_e32 v53, vcc, 0, v103, vcc
	ds_read2st64_b32 v[50:51], v104 offset0:4 offset1:5
	v_mul_f32_e32 v52, 0xbfb8aa3b, v67
	v_mul_f32_e32 v53, 0xbfb8aa3b, v73
	v_exp_f32_e32 v52, v52
	v_exp_f32_e32 v53, v53
	s_waitcnt lgkmcnt(0)
	v_pk_mul_f32 v[50:51], v[72:73], v[50:51] op_sel_hi:[0,1]
	v_pk_fma_f32 v[50:51], v[54:55], v[66:67], v[50:51] op_sel_hi:[1,0,1]
	v_pk_add_f32 v[52:53], v[52:53], 1.0 op_sel_hi:[1,0]
	s_nop 0
	v_div_scale_f32 v54, s[0:1], v53, v53, v73
	v_rcp_f32_e32 v55, v54
	v_pk_mul_f32 v[50:51], v[0:1], v[50:51] op_sel_hi:[0,1]
	v_fma_f32 v100, -v54, v55, 1.0
	v_fmac_f32_e32 v55, v100, v55
	v_div_scale_f32 v100, vcc, v73, v53, v73
	v_mul_f32_e32 v102, v100, v55
	v_fma_f32 v103, -v54, v102, v100
	v_fmac_f32_e32 v102, v103, v55
	v_fma_f32 v54, -v54, v102, v100
	v_div_fmas_f32 v54, v54, v55, v102
	v_div_fixup_f32 v53, v54, v53, v73
	v_rcp_f32_e32 v55, v52
	s_nop 0
	v_mul_f32_e32 v52, v67, v55
	v_lshlrev_b32_e32 v67, 16, v153
	v_and_b32_e32 v73, 0xffff0000, v153
	v_pk_mul_f32 v[50:51], v[52:53], v[50:51]
	ds_read2st64_b32 v[52:53], v104 offset0:6 offset1:7
	v_mul_f32_e32 v54, 0xbfb8aa3b, v67
	v_mul_f32_e32 v55, 0xbfb8aa3b, v73
	v_exp_f32_e32 v54, v54
	v_exp_f32_e32 v55, v55
	s_waitcnt lgkmcnt(0)
	v_pk_mul_f32 v[52:53], v[72:73], v[52:53] op_sel_hi:[0,1]
	v_pk_fma_f32 v[52:53], v[56:57], v[66:67], v[52:53] op_sel_hi:[1,0,1]
	v_cvt_pk_bf16_f32 v118, v50, v51
	v_pk_add_f32 v[54:55], v[54:55], 1.0 op_sel_hi:[1,0]
	v_pk_mul_f32 v[52:53], v[0:1], v[52:53] op_sel_hi:[0,1]
	v_rcp_f32_e32 v57, v55
	s_nop 0
	v_mul_f32_e32 v55, v73, v57
	v_rcp_f32_e32 v57, v54
	s_nop 0
	v_mul_f32_e32 v54, v67, v57
	v_pk_mul_f32 v[52:53], v[54:55], v[52:53]
	v_lshlrev_b32_e32 v54, 16, v154
	v_and_b32_e32 v55, 0xffff0000, v154
	v_cvt_pk_bf16_f32 v119, v52, v53
	v_mul_f32_e32 v52, 0xbfb8aa3b, v54
	v_mul_f32_e32 v53, 0xbfb8aa3b, v55
	v_exp_f32_e32 v52, v52
	v_exp_f32_e32 v53, v53
	v_lshlrev_b32_e32 v150, 1, v182
	v_mov_b32_e32 v151, 0
	v_lshl_add_u64 v[148:149], v[150:151], 0, v[68:69]
	s_nop 1
	v_permlane32_swap_b32_e32 v116, v118
	v_permlane32_swap_b32_e32 v117, v119
	global_store_dwordx4 v[148:149], v[116:119], off
	ds_read2st64_b32 v[50:51], v104 offset0:8 offset1:9
	v_pk_add_f32 v[52:53], v[52:53], 1.0 op_sel_hi:[1,0]
	s_nop 0
	v_div_scale_f32 v56, s[0:1], v53, v53, v55
	v_rcp_f32_e32 v57, v56
	s_waitcnt lgkmcnt(0)
; DI unsigned pk2(float lo, float hi) { f32x2 v = {lo, hi}; return __builtin_bit_cast(unsigned, __builtin_convertvector(v, bf2_t)); }
; DI float bflo(unsigned w) { return __uint_as_float(w << 16); }
; DI float bfhi(unsigned w) { return __uint_as_float(w & 0xffff0000u); }
; DI void attn_unit(const Params& p, int b, int h, int qb, LAS unsigned char* lds, int tid, int lane, int wave) {
;     ...
; #pragma unroll
;         for (int i = 0; i < 4; ++i)
; #pragma unroll
;             for (int q = 0; q < 4; ++q) {
;                 float gv[4] = {bflo(gw[i][q].x), bfhi(gw[i][q].x), bflo(gw[i][q].y), bfhi(gw[i][q].y)}; float ov[4];
; #pragma unroll
;                 for (int e = 0; e < 4; ++e) { const float val = (o[i][q * 4 + e] * a0 + MB[(i * 16 + q * 4 + e) * 64] * a1) * inv; ov[e] = val * (gv[e] / (1.f + __expf(-gv[e]))); }
;                 *(u32x2*)(op + i * 32 + q * 8) = (u32x2){pk2(ov[0], ov[1]), pk2(ov[2], ov[3])};
;             }
	v_pk_mul_f32 v[50:51], v[72:73], v[50:51] op_sel_hi:[0,1]
	v_pk_fma_f32 v[50:51], v[58:59], v[66:67], v[50:51] op_sel_hi:[1,0,1]
	v_fma_f32 v58, -v56, v57, 1.0
	v_fmac_f32_e32 v57, v58, v57
	v_div_scale_f32 v58, vcc, v55, v53, v55
	v_mul_f32_e32 v59, v58, v57
	v_fma_f32 v67, -v56, v59, v58
	v_fmac_f32_e32 v59, v67, v57
	v_fma_f32 v56, -v56, v59, v58
	v_div_fmas_f32 v56, v56, v57, v59
	v_div_fixup_f32 v53, v56, v53, v55
	v_div_scale_f32 v55, s[0:1], v52, v52, v54
	v_rcp_f32_e32 v56, v55
	v_pk_mul_f32 v[50:51], v[0:1], v[50:51] op_sel_hi:[0,1]
	v_fma_f32 v57, -v55, v56, 1.0
	v_fmac_f32_e32 v56, v57, v56
	v_div_scale_f32 v57, vcc, v54, v52, v54
	v_mul_f32_e32 v58, v57, v56
	v_fma_f32 v59, -v55, v58, v57
	v_fmac_f32_e32 v58, v59, v56
	v_fma_f32 v55, -v55, v58, v57
	v_div_fmas_f32 v55, v55, v56, v58
	v_lshlrev_b32_e32 v56, 16, v155
	v_and_b32_e32 v57, 0xffff0000, v155
	v_div_fixup_f32 v52, v55, v52, v54
	v_mul_f32_e32 v54, 0xbfb8aa3b, v56
	v_mul_f32_e32 v55, 0xbfb8aa3b, v57
	v_exp_f32_e32 v54, v54
	v_exp_f32_e32 v55, v55
	v_pk_mul_f32 v[50:51], v[52:53], v[50:51]
	ds_read2st64_b32 v[52:53], v104 offset0:10 offset1:11
	v_cvt_pk_bf16_f32 v120, v50, v51
	v_pk_add_f32 v[54:55], v[54:55], 1.0 op_sel_hi:[1,0]
	s_waitcnt lgkmcnt(0)
	v_pk_mul_f32 v[52:53], v[72:73], v[52:53] op_sel_hi:[0,1]
	v_div_scale_f32 v58, s[0:1], v55, v55, v57
	v_rcp_f32_e32 v59, v58
	v_pk_fma_f32 v[52:53], v[60:61], v[66:67], v[52:53] op_sel_hi:[1,0,1]
	v_fma_f32 v60, -v58, v59, 1.0
	v_fmac_f32_e32 v59, v60, v59
	v_div_scale_f32 v60, vcc, v57, v55, v57
	v_mul_f32_e32 v61, v60, v59
	v_fma_f32 v67, -v58, v61, v60
	v_fmac_f32_e32 v61, v67, v59
	v_fma_f32 v58, -v58, v61, v60
	v_div_fmas_f32 v58, v58, v59, v61
	v_div_fixup_f32 v55, v58, v55, v57
	v_div_scale_f32 v57, s[0:1], v54, v54, v56
	v_rcp_f32_e32 v58, v57
	v_pk_mul_f32 v[52:53], v[0:1], v[52:53] op_sel_hi:[0,1]
	v_fma_f32 v59, -v57, v58, 1.0
	v_fmac_f32_e32 v58, v59, v58
	v_div_scale_f32 v59, vcc, v56, v54, v56
	v_mul_f32_e32 v60, v59, v58
	v_fma_f32 v61, -v57, v60, v59
	v_fmac_f32_e32 v60, v61, v58
	v_fma_f32 v57, -v57, v60, v59
	v_div_fmas_f32 v57, v57, v58, v60
	v_div_fixup_f32 v54, v57, v54, v56
	v_pk_mul_f32 v[52:53], v[54:55], v[52:53]
	v_lshlrev_b32_e32 v54, 16, v156
	v_and_b32_e32 v55, 0xffff0000, v156
	v_cvt_pk_bf16_f32 v121, v52, v53
	v_mul_f32_e32 v52, 0xbfb8aa3b, v54
	v_mul_f32_e32 v53, 0xbfb8aa3b, v55
	v_exp_f32_e32 v52, v52
	v_exp_f32_e32 v53, v53
	ds_read2st64_b32 v[50:51], v104 offset0:12 offset1:13
	v_pk_add_f32 v[52:53], v[52:53], 1.0 op_sel_hi:[1,0]
	s_nop 0
	v_div_scale_f32 v56, s[0:1], v53, v53, v55
	v_rcp_f32_e32 v57, v56
	s_waitcnt lgkmcnt(0)
	v_pk_mul_f32 v[50:51], v[72:73], v[50:51] op_sel_hi:[0,1]
	v_pk_fma_f32 v[50:51], v[62:63], v[66:67], v[50:51] op_sel_hi:[1,0,1]
	v_fma_f32 v58, -v56, v57, 1.0
	v_fmac_f32_e32 v57, v58, v57
	v_div_scale_f32 v58, vcc, v55, v53, v55
	v_mul_f32_e32 v59, v58, v57
	v_fma_f32 v60, -v56, v59, v58
	v_fmac_f32_e32 v59, v60, v57
	v_fma_f32 v56, -v56, v59, v58
	v_div_fmas_f32 v56, v56, v57, v59
	v_div_fixup_f32 v53, v56, v53, v55
	v_div_scale_f32 v55, s[0:1], v52, v52, v54
	v_rcp_f32_e32 v56, v55
	v_pk_mul_f32 v[50:51], v[0:1], v[50:51] op_sel_hi:[0,1]
	v_fma_f32 v57, -v55, v56, 1.0
	v_fmac_f32_e32 v56, v57, v56
	v_div_scale_f32 v57, vcc, v54, v52, v54
	v_mul_f32_e32 v58, v57, v56
	v_fma_f32 v59, -v55, v58, v57
	v_fmac_f32_e32 v58, v59, v56
	v_fma_f32 v55, -v55, v58, v57
	v_div_fmas_f32 v55, v55, v56, v58
	v_lshlrev_b32_e32 v56, 16, v157
	v_and_b32_e32 v57, 0xffff0000, v157
	v_div_fixup_f32 v52, v55, v52, v54
	v_mul_f32_e32 v54, 0xbfb8aa3b, v56
	v_mul_f32_e32 v55, 0xbfb8aa3b, v57
	v_exp_f32_e32 v54, v54
	v_exp_f32_e32 v55, v55
	v_pk_mul_f32 v[50:51], v[52:53], v[50:51]
	ds_read2st64_b32 v[52:53], v104 offset0:14 offset1:15
	v_cvt_pk_bf16_f32 v122, v50, v51
	v_pk_add_f32 v[54:55], v[54:55], 1.0 op_sel_hi:[1,0]
	s_waitcnt lgkmcnt(0)
	v_pk_mul_f32 v[52:53], v[72:73], v[52:53] op_sel_hi:[0,1]
	v_div_scale_f32 v58, s[0:1], v55, v55, v57
	v_rcp_f32_e32 v59, v58
	v_pk_fma_f32 v[52:53], v[64:65], v[66:67], v[52:53] op_sel_hi:[1,0,1]
	v_fma_f32 v60, -v58, v59, 1.0
	v_fmac_f32_e32 v59, v60, v59
	v_div_scale_f32 v60, vcc, v57, v55, v57
	v_mul_f32_e32 v61, v60, v59
	v_fma_f32 v62, -v58, v61, v60
	v_fmac_f32_e32 v61, v62, v59
	v_fma_f32 v58, -v58, v61, v60
	v_div_fmas_f32 v58, v58, v59, v61
	v_div_fixup_f32 v55, v58, v55, v57
	v_div_scale_f32 v57, s[0:1], v54, v54, v56
	v_rcp_f32_e32 v58, v57
	v_pk_mul_f32 v[52:53], v[0:1], v[52:53] op_sel_hi:[0,1]
	v_fma_f32 v59, -v57, v58, 1.0
	v_fmac_f32_e32 v58, v59, v58
	v_div_scale_f32 v59, vcc, v56, v54, v56
	v_mul_f32_e32 v60, v59, v58
	v_fma_f32 v61, -v57, v60, v59
	v_fmac_f32_e32 v60, v61, v58
	v_fma_f32 v57, -v57, v60, v59
	v_div_fmas_f32 v57, v57, v58, v60
	v_div_fixup_f32 v54, v57, v54, v56
	v_pk_mul_f32 v[52:53], v[54:55], v[52:53]
	v_lshlrev_b32_e32 v54, 16, v158
	v_cvt_pk_bf16_f32 v123, v52, v53
	s_nop 1
	v_permlane32_swap_b32_e32 v120, v122
	v_permlane32_swap_b32_e32 v121, v123
	global_store_dwordx4 v[148:149], v[120:123], off offset:32
	ds_read2st64_b32 v[50:51], v104 offset0:16 offset1:17
	v_and_b32_e32 v55, 0xffff0000, v158
	v_mul_f32_e32 v52, 0xbfb8aa3b, v54
	v_exp_f32_e32 v52, v52
	s_waitcnt lgkmcnt(0)
	v_pk_mul_f32 v[50:51], v[72:73], v[50:51] op_sel_hi:[0,1]
	v_pk_fma_f32 v[34:35], v[34:35], v[66:67], v[50:51] op_sel_hi:[1,0,1]
	v_mul_f32_e32 v50, 0xbfb8aa3b, v55
	v_exp_f32_e32 v53, v50
	v_pk_mul_f32 v[34:35], v[0:1], v[34:35] op_sel_hi:[0,1]
	v_pk_add_f32 v[50:51], v[52:53], 1.0 op_sel_hi:[1,0]
	s_nop 0
	v_rcp_f32_e32 v53, v51
	s_nop 0
	v_mul_f32_e32 v51, v55, v53
	v_rcp_f32_e32 v53, v50
	s_nop 0
	v_mul_f32_e32 v50, v54, v53
	v_pk_mul_f32 v[34:35], v[50:51], v[34:35]
	ds_read2st64_b32 v[50:51], v104 offset0:18 offset1:19
	v_lshlrev_b32_e32 v54, 16, v159
	v_and_b32_e32 v55, 0xffff0000, v159
	v_mul_f32_e32 v52, 0xbfb8aa3b, v54
	v_exp_f32_e32 v52, v52
	s_waitcnt lgkmcnt(0)
; DI unsigned pk2(float lo, float hi) { f32x2 v = {lo, hi}; return __builtin_bit_cast(unsigned, __builtin_convertvector(v, bf2_t)); }
; DI float bflo(unsigned w) { return __uint_as_float(w << 16); }
; DI float bfhi(unsigned w) { return __uint_as_float(w & 0xffff0000u); }
; DI void attn_unit(const Params& p, int b, int h, int qb, LAS unsigned char* lds, int tid, int lane, int wave) {
;     ...
; #pragma unroll
;         for (int i = 0; i < 4; ++i)
; #pragma unroll
;             for (int q = 0; q < 4; ++q) {
;                 float gv[4] = {bflo(gw[i][q].x), bfhi(gw[i][q].x), bflo(gw[i][q].y), bfhi(gw[i][q].y)}; float ov[4];
; #pragma unroll
;                 for (int e = 0; e < 4; ++e) { const float val = (o[i][q * 4 + e] * a0 + MB[(i * 16 + q * 4 + e) * 64] * a1) * inv; ov[e] = val * (gv[e] / (1.f + __expf(-gv[e]))); }
;                 *(u32x2*)(op + i * 32 + q * 8) = (u32x2){pk2(ov[0], ov[1]), pk2(ov[2], ov[3])};
;             }
	v_pk_mul_f32 v[50:51], v[72:73], v[50:51] op_sel_hi:[0,1]
	v_pk_fma_f32 v[36:37], v[36:37], v[66:67], v[50:51] op_sel_hi:[1,0,1]
	v_mul_f32_e32 v50, 0xbfb8aa3b, v55
	v_exp_f32_e32 v53, v50
	v_pk_mul_f32 v[36:37], v[0:1], v[36:37] op_sel_hi:[0,1]
	v_cvt_pk_bf16_f32 v124, v34, v35
	v_pk_add_f32 v[50:51], v[52:53], 1.0 op_sel_hi:[1,0]
	s_nop 0
	v_rcp_f32_e32 v53, v51
	s_nop 0
	v_mul_f32_e32 v51, v55, v53
	v_rcp_f32_e32 v53, v50
	s_nop 0
	v_mul_f32_e32 v50, v54, v53
	v_pk_mul_f32 v[36:37], v[50:51], v[36:37]
	v_lshlrev_b32_e32 v50, 16, v160
	v_cvt_pk_bf16_f32 v125, v36, v37
	v_and_b32_e32 v51, 0xffff0000, v160
	ds_read2st64_b32 v[34:35], v104 offset0:20 offset1:21
	v_mul_f32_e32 v36, 0xbfb8aa3b, v50
	v_mul_f32_e32 v37, 0xbfb8aa3b, v51
	v_exp_f32_e32 v36, v36
	v_exp_f32_e32 v37, v37
	s_waitcnt lgkmcnt(0)
	v_pk_mul_f32 v[34:35], v[72:73], v[34:35] op_sel_hi:[0,1]
	v_pk_fma_f32 v[34:35], v[38:39], v[66:67], v[34:35] op_sel_hi:[1,0,1]
	v_pk_add_f32 v[36:37], v[36:37], 1.0 op_sel_hi:[1,0]
	s_nop 0
	v_div_scale_f32 v38, s[0:1], v37, v37, v51
	v_rcp_f32_e32 v39, v38
	v_pk_mul_f32 v[34:35], v[0:1], v[34:35] op_sel_hi:[0,1]
	v_fma_f32 v52, -v38, v39, 1.0
	v_fmac_f32_e32 v39, v52, v39
	v_div_scale_f32 v52, vcc, v51, v37, v51
	v_mul_f32_e32 v53, v52, v39
	v_fma_f32 v54, -v38, v53, v52
	v_fmac_f32_e32 v53, v54, v39
	v_fma_f32 v38, -v38, v53, v52
	v_div_fmas_f32 v38, v38, v39, v53
	v_div_fixup_f32 v37, v38, v37, v51
	v_rcp_f32_e32 v39, v36
	s_nop 0
	v_mul_f32_e32 v36, v50, v39
	v_lshlrev_b32_e32 v50, 16, v161
	v_and_b32_e32 v51, 0xffff0000, v161
	v_pk_mul_f32 v[34:35], v[36:37], v[34:35]
	ds_read2st64_b32 v[36:37], v104 offset0:22 offset1:23
	v_mul_f32_e32 v38, 0xbfb8aa3b, v50
	v_mul_f32_e32 v39, 0xbfb8aa3b, v51
	v_exp_f32_e32 v38, v38
	v_exp_f32_e32 v39, v39
	s_waitcnt lgkmcnt(0)
	v_pk_mul_f32 v[36:37], v[72:73], v[36:37] op_sel_hi:[0,1]
	v_pk_fma_f32 v[36:37], v[40:41], v[66:67], v[36:37] op_sel_hi:[1,0,1]
	v_cvt_pk_bf16_f32 v126, v34, v35
	v_pk_add_f32 v[38:39], v[38:39], 1.0 op_sel_hi:[1,0]
	v_pk_mul_f32 v[36:37], v[0:1], v[36:37] op_sel_hi:[0,1]
	v_rcp_f32_e32 v41, v39
	s_nop 0
	v_mul_f32_e32 v39, v51, v41
	v_rcp_f32_e32 v41, v38
	s_nop 0
	v_mul_f32_e32 v38, v50, v41
	v_pk_mul_f32 v[36:37], v[38:39], v[36:37]
	v_lshlrev_b32_e32 v38, 16, v162
	v_and_b32_e32 v39, 0xffff0000, v162
	v_cvt_pk_bf16_f32 v127, v36, v37
	v_mul_f32_e32 v36, 0xbfb8aa3b, v38
	v_mul_f32_e32 v37, 0xbfb8aa3b, v39
	v_exp_f32_e32 v36, v36
	v_exp_f32_e32 v37, v37
	s_nop 1
	v_permlane32_swap_b32_e32 v124, v126
	v_permlane32_swap_b32_e32 v125, v127
	global_store_dwordx4 v[148:149], v[124:127], off offset:64
	ds_read2st64_b32 v[34:35], v104 offset0:24 offset1:25
	v_pk_add_f32 v[36:37], v[36:37], 1.0 op_sel_hi:[1,0]
	s_nop 0
	v_div_scale_f32 v40, s[0:1], v37, v37, v39
	v_rcp_f32_e32 v41, v40
	s_waitcnt lgkmcnt(0)
	v_pk_mul_f32 v[34:35], v[72:73], v[34:35] op_sel_hi:[0,1]
	v_pk_fma_f32 v[34:35], v[42:43], v[66:67], v[34:35] op_sel_hi:[1,0,1]
	v_fma_f32 v42, -v40, v41, 1.0
	v_fmac_f32_e32 v41, v42, v41
	v_div_scale_f32 v42, vcc, v39, v37, v39
	v_mul_f32_e32 v43, v42, v41
	v_fma_f32 v50, -v40, v43, v42
	v_fmac_f32_e32 v43, v50, v41
	v_fma_f32 v40, -v40, v43, v42
	v_div_fmas_f32 v40, v40, v41, v43
	v_div_fixup_f32 v37, v40, v37, v39
	v_div_scale_f32 v39, s[0:1], v36, v36, v38
	v_rcp_f32_e32 v40, v39
	v_pk_mul_f32 v[34:35], v[0:1], v[34:35] op_sel_hi:[0,1]
	v_fma_f32 v41, -v39, v40, 1.0
	v_fmac_f32_e32 v40, v41, v40
	v_div_scale_f32 v41, vcc, v38, v36, v38
	v_mul_f32_e32 v42, v41, v40
	v_fma_f32 v43, -v39, v42, v41
	v_fmac_f32_e32 v42, v43, v40
	v_fma_f32 v39, -v39, v42, v41
	v_div_fmas_f32 v39, v39, v40, v42
	v_lshlrev_b32_e32 v40, 16, v163
	v_and_b32_e32 v41, 0xffff0000, v163
	v_div_fixup_f32 v36, v39, v36, v38
	v_mul_f32_e32 v38, 0xbfb8aa3b, v40
	v_mul_f32_e32 v39, 0xbfb8aa3b, v41
	v_exp_f32_e32 v38, v38
	v_exp_f32_e32 v39, v39
	v_pk_mul_f32 v[34:35], v[36:37], v[34:35]
	ds_read2st64_b32 v[36:37], v104 offset0:26 offset1:27
	v_cvt_pk_bf16_f32 v128, v34, v35
	v_pk_add_f32 v[38:39], v[38:39], 1.0 op_sel_hi:[1,0]
	s_waitcnt lgkmcnt(0)
	v_pk_mul_f32 v[36:37], v[72:73], v[36:37] op_sel_hi:[0,1]
	v_div_scale_f32 v42, s[0:1], v39, v39, v41
	v_rcp_f32_e32 v43, v42
	v_pk_fma_f32 v[36:37], v[44:45], v[66:67], v[36:37] op_sel_hi:[1,0,1]
	v_fma_f32 v44, -v42, v43, 1.0
	v_fmac_f32_e32 v43, v44, v43
	v_div_scale_f32 v44, vcc, v41, v39, v41
	v_mul_f32_e32 v45, v44, v43
	v_fma_f32 v50, -v42, v45, v44
	v_fmac_f32_e32 v45, v50, v43
	v_fma_f32 v42, -v42, v45, v44
	v_div_fmas_f32 v42, v42, v43, v45
	v_div_fixup_f32 v39, v42, v39, v41
	v_div_scale_f32 v41, s[0:1], v38, v38, v40
	v_rcp_f32_e32 v42, v41
	v_pk_mul_f32 v[36:37], v[0:1], v[36:37] op_sel_hi:[0,1]
	v_fma_f32 v43, -v41, v42, 1.0
	v_fmac_f32_e32 v42, v43, v42
	v_div_scale_f32 v43, vcc, v40, v38, v40
	v_mul_f32_e32 v44, v43, v42
	v_fma_f32 v45, -v41, v44, v43
	v_fmac_f32_e32 v44, v45, v42
	v_fma_f32 v41, -v41, v44, v43
	v_div_fmas_f32 v41, v41, v42, v44
	v_div_fixup_f32 v38, v41, v38, v40
	v_pk_mul_f32 v[36:37], v[38:39], v[36:37]
	v_lshlrev_b32_e32 v38, 16, v164
	v_and_b32_e32 v39, 0xffff0000, v164
	v_cvt_pk_bf16_f32 v129, v36, v37
	v_mul_f32_e32 v36, 0xbfb8aa3b, v38
	v_mul_f32_e32 v37, 0xbfb8aa3b, v39
	v_exp_f32_e32 v36, v36
	v_exp_f32_e32 v37, v37
	ds_read2st64_b32 v[34:35], v104 offset0:28 offset1:29
	v_pk_add_f32 v[36:37], v[36:37], 1.0 op_sel_hi:[1,0]
	s_nop 0
	v_div_scale_f32 v40, s[0:1], v37, v37, v39
	v_rcp_f32_e32 v41, v40
	s_waitcnt lgkmcnt(0)
; DI unsigned pk2(float lo, float hi) { f32x2 v = {lo, hi}; return __builtin_bit_cast(unsigned, __builtin_convertvector(v, bf2_t)); }
; DI float bflo(unsigned w) { return __uint_as_float(w << 16); }
; DI float bfhi(unsigned w) { return __uint_as_float(w & 0xffff0000u); }
; DI void attn_unit(const Params& p, int b, int h, int qb, LAS unsigned char* lds, int tid, int lane, int wave) {
;     ...
; #pragma unroll
;         for (int i = 0; i < 4; ++i)
; #pragma unroll
;             for (int q = 0; q < 4; ++q) {
;                 float gv[4] = {bflo(gw[i][q].x), bfhi(gw[i][q].x), bflo(gw[i][q].y), bfhi(gw[i][q].y)}; float ov[4];
; #pragma unroll
;                 for (int e = 0; e < 4; ++e) { const float val = (o[i][q * 4 + e] * a0 + MB[(i * 16 + q * 4 + e) * 64] * a1) * inv; ov[e] = val * (gv[e] / (1.f + __expf(-gv[e]))); }
;                 *(u32x2*)(op + i * 32 + q * 8) = (u32x2){pk2(ov[0], ov[1]), pk2(ov[2], ov[3])};
;             }
	v_pk_mul_f32 v[34:35], v[72:73], v[34:35] op_sel_hi:[0,1]
	v_pk_fma_f32 v[34:35], v[46:47], v[66:67], v[34:35] op_sel_hi:[1,0,1]
	v_fma_f32 v42, -v40, v41, 1.0
	v_fmac_f32_e32 v41, v42, v41
	v_div_scale_f32 v42, vcc, v39, v37, v39
	v_mul_f32_e32 v43, v42, v41
	v_fma_f32 v44, -v40, v43, v42
	v_fmac_f32_e32 v43, v44, v41
	v_fma_f32 v40, -v40, v43, v42
	v_div_fmas_f32 v40, v40, v41, v43
	v_div_fixup_f32 v37, v40, v37, v39
	v_div_scale_f32 v39, s[0:1], v36, v36, v38
	v_rcp_f32_e32 v40, v39
	v_pk_mul_f32 v[34:35], v[0:1], v[34:35] op_sel_hi:[0,1]
	v_fma_f32 v41, -v39, v40, 1.0
	v_fmac_f32_e32 v40, v41, v40
	v_div_scale_f32 v41, vcc, v38, v36, v38
	v_mul_f32_e32 v42, v41, v40
	v_fma_f32 v43, -v39, v42, v41
	v_fmac_f32_e32 v42, v43, v40
	v_fma_f32 v39, -v39, v42, v41
	v_div_fmas_f32 v39, v39, v40, v42
	v_lshlrev_b32_e32 v40, 16, v165
	v_and_b32_e32 v41, 0xffff0000, v165
	v_div_fixup_f32 v36, v39, v36, v38
	v_mul_f32_e32 v38, 0xbfb8aa3b, v40
	v_mul_f32_e32 v39, 0xbfb8aa3b, v41
	v_exp_f32_e32 v38, v38
	v_exp_f32_e32 v39, v39
	v_pk_mul_f32 v[34:35], v[36:37], v[34:35]
	ds_read2st64_b32 v[36:37], v104 offset0:30 offset1:31
	v_cvt_pk_bf16_f32 v130, v34, v35
	v_pk_add_f32 v[38:39], v[38:39], 1.0 op_sel_hi:[1,0]
	s_waitcnt lgkmcnt(0)
	v_pk_mul_f32 v[36:37], v[72:73], v[36:37] op_sel_hi:[0,1]
	v_div_scale_f32 v42, s[0:1], v39, v39, v41
	v_rcp_f32_e32 v43, v42
	v_pk_fma_f32 v[36:37], v[48:49], v[66:67], v[36:37] op_sel_hi:[1,0,1]
	v_fma_f32 v44, -v42, v43, 1.0
	v_fmac_f32_e32 v43, v44, v43
	v_div_scale_f32 v44, vcc, v41, v39, v41
	v_mul_f32_e32 v45, v44, v43
	v_fma_f32 v46, -v42, v45, v44
	v_fmac_f32_e32 v45, v46, v43
	v_fma_f32 v42, -v42, v45, v44
	v_div_fmas_f32 v42, v42, v43, v45
	v_div_fixup_f32 v39, v42, v39, v41
	v_div_scale_f32 v41, s[0:1], v38, v38, v40
	v_rcp_f32_e32 v42, v41
	v_pk_mul_f32 v[36:37], v[0:1], v[36:37] op_sel_hi:[0,1]
	v_fma_f32 v43, -v41, v42, 1.0
	v_fmac_f32_e32 v42, v43, v42
	v_div_scale_f32 v43, vcc, v40, v38, v40
	v_mul_f32_e32 v44, v43, v42
	v_fma_f32 v45, -v41, v44, v43
	v_fmac_f32_e32 v44, v45, v42
	v_fma_f32 v41, -v41, v44, v43
	v_div_fmas_f32 v41, v41, v42, v44
	v_div_fixup_f32 v38, v41, v38, v40
	v_pk_mul_f32 v[36:37], v[38:39], v[36:37]
	v_lshlrev_b32_e32 v38, 16, v166
	v_cvt_pk_bf16_f32 v131, v36, v37
	s_nop 1
	v_permlane32_swap_b32_e32 v128, v130
	v_permlane32_swap_b32_e32 v129, v131
	global_store_dwordx4 v[148:149], v[128:131], off offset:96
	ds_read2st64_b32 v[34:35], v104 offset0:32 offset1:33
	v_and_b32_e32 v39, 0xffff0000, v166
	v_mul_f32_e32 v36, 0xbfb8aa3b, v38
	v_exp_f32_e32 v36, v36
	s_waitcnt lgkmcnt(0)
	v_pk_mul_f32 v[34:35], v[72:73], v[34:35] op_sel_hi:[0,1]
	v_pk_fma_f32 v[18:19], v[18:19], v[66:67], v[34:35] op_sel_hi:[1,0,1]
	v_mul_f32_e32 v34, 0xbfb8aa3b, v39
	v_exp_f32_e32 v37, v34
	v_pk_mul_f32 v[18:19], v[0:1], v[18:19] op_sel_hi:[0,1]
	v_pk_add_f32 v[34:35], v[36:37], 1.0 op_sel_hi:[1,0]
	s_nop 0
	v_rcp_f32_e32 v37, v35
	s_nop 0
	v_mul_f32_e32 v35, v39, v37
	v_rcp_f32_e32 v37, v34
	s_nop 0
	v_mul_f32_e32 v34, v38, v37
	v_pk_mul_f32 v[18:19], v[34:35], v[18:19]
	ds_read2st64_b32 v[34:35], v104 offset0:34 offset1:35
	v_lshlrev_b32_e32 v38, 16, v167
	v_and_b32_e32 v39, 0xffff0000, v167
	v_mul_f32_e32 v36, 0xbfb8aa3b, v38
	v_exp_f32_e32 v36, v36
	s_waitcnt lgkmcnt(0)
	v_pk_mul_f32 v[34:35], v[72:73], v[34:35] op_sel_hi:[0,1]
	v_pk_fma_f32 v[20:21], v[20:21], v[66:67], v[34:35] op_sel_hi:[1,0,1]
	v_mul_f32_e32 v34, 0xbfb8aa3b, v39
	v_exp_f32_e32 v37, v34
	v_pk_mul_f32 v[20:21], v[0:1], v[20:21] op_sel_hi:[0,1]
	v_cvt_pk_bf16_f32 v132, v18, v19
	v_pk_add_f32 v[34:35], v[36:37], 1.0 op_sel_hi:[1,0]
	s_nop 0
	v_rcp_f32_e32 v37, v35
	s_nop 0
	v_mul_f32_e32 v35, v39, v37
	v_rcp_f32_e32 v37, v34
	s_nop 0
	v_mul_f32_e32 v34, v38, v37
	v_pk_mul_f32 v[20:21], v[34:35], v[20:21]
	v_lshlrev_b32_e32 v34, 16, v168
	v_cvt_pk_bf16_f32 v133, v20, v21
	v_and_b32_e32 v35, 0xffff0000, v168
	ds_read2st64_b32 v[18:19], v104 offset0:36 offset1:37
	v_mul_f32_e32 v20, 0xbfb8aa3b, v34
	v_mul_f32_e32 v21, 0xbfb8aa3b, v35
	v_exp_f32_e32 v20, v20
	v_exp_f32_e32 v21, v21
	s_waitcnt lgkmcnt(0)
	v_pk_mul_f32 v[18:19], v[72:73], v[18:19] op_sel_hi:[0,1]
	v_pk_fma_f32 v[18:19], v[22:23], v[66:67], v[18:19] op_sel_hi:[1,0,1]
	v_pk_add_f32 v[20:21], v[20:21], 1.0 op_sel_hi:[1,0]
	s_nop 0
	v_div_scale_f32 v22, s[0:1], v21, v21, v35
	v_rcp_f32_e32 v23, v22
	v_pk_mul_f32 v[18:19], v[0:1], v[18:19] op_sel_hi:[0,1]
	v_fma_f32 v36, -v22, v23, 1.0
	v_fmac_f32_e32 v23, v36, v23
	v_div_scale_f32 v36, vcc, v35, v21, v35
	v_mul_f32_e32 v37, v36, v23
	v_fma_f32 v38, -v22, v37, v36
	v_fmac_f32_e32 v37, v38, v23
	v_fma_f32 v22, -v22, v37, v36
	v_div_fmas_f32 v22, v22, v23, v37
	v_div_fixup_f32 v21, v22, v21, v35
	v_rcp_f32_e32 v23, v20
	s_nop 0
	v_mul_f32_e32 v20, v34, v23
	v_lshlrev_b32_e32 v34, 16, v169
	v_and_b32_e32 v35, 0xffff0000, v169
	v_pk_mul_f32 v[18:19], v[20:21], v[18:19]
	ds_read2st64_b32 v[20:21], v104 offset0:38 offset1:39
	v_mul_f32_e32 v22, 0xbfb8aa3b, v34
	v_mul_f32_e32 v23, 0xbfb8aa3b, v35
	v_exp_f32_e32 v22, v22
	v_exp_f32_e32 v23, v23
	s_waitcnt lgkmcnt(0)
	v_pk_mul_f32 v[20:21], v[72:73], v[20:21] op_sel_hi:[0,1]
	v_pk_fma_f32 v[20:21], v[24:25], v[66:67], v[20:21] op_sel_hi:[1,0,1]
	v_cvt_pk_bf16_f32 v134, v18, v19
	v_pk_add_f32 v[22:23], v[22:23], 1.0 op_sel_hi:[1,0]
	v_pk_mul_f32 v[20:21], v[0:1], v[20:21] op_sel_hi:[0,1]
	v_rcp_f32_e32 v25, v23
	s_nop 0
	v_mul_f32_e32 v23, v35, v25
	v_rcp_f32_e32 v25, v22
	s_nop 0
	v_mul_f32_e32 v22, v34, v25
	v_pk_mul_f32 v[20:21], v[22:23], v[20:21]
	v_lshlrev_b32_e32 v22, 16, v170
	v_and_b32_e32 v23, 0xffff0000, v170
	v_cvt_pk_bf16_f32 v135, v20, v21
	v_mul_f32_e32 v20, 0xbfb8aa3b, v22
	v_mul_f32_e32 v21, 0xbfb8aa3b, v23
	v_exp_f32_e32 v20, v20
	v_exp_f32_e32 v21, v21
	s_nop 1
	v_permlane32_swap_b32_e32 v132, v134
	v_permlane32_swap_b32_e32 v133, v135
	global_store_dwordx4 v[148:149], v[132:135], off offset:128
	ds_read2st64_b32 v[18:19], v104 offset0:40 offset1:41
	v_pk_add_f32 v[20:21], v[20:21], 1.0 op_sel_hi:[1,0]
	s_nop 0
	v_div_scale_f32 v24, s[0:1], v21, v21, v23
	v_rcp_f32_e32 v25, v24
	s_waitcnt lgkmcnt(0)
; DI unsigned pk2(float lo, float hi) { f32x2 v = {lo, hi}; return __builtin_bit_cast(unsigned, __builtin_convertvector(v, bf2_t)); }
; DI float bflo(unsigned w) { return __uint_as_float(w << 16); }
; DI float bfhi(unsigned w) { return __uint_as_float(w & 0xffff0000u); }
; DI void attn_unit(const Params& p, int b, int h, int qb, LAS unsigned char* lds, int tid, int lane, int wave) {
;     ...
; #pragma unroll
;         for (int i = 0; i < 4; ++i)
; #pragma unroll
;             for (int q = 0; q < 4; ++q) {
;                 float gv[4] = {bflo(gw[i][q].x), bfhi(gw[i][q].x), bflo(gw[i][q].y), bfhi(gw[i][q].y)}; float ov[4];
; #pragma unroll
;                 for (int e = 0; e < 4; ++e) { const float val = (o[i][q * 4 + e] * a0 + MB[(i * 16 + q * 4 + e) * 64] * a1) * inv; ov[e] = val * (gv[e] / (1.f + __expf(-gv[e]))); }
;                 *(u32x2*)(op + i * 32 + q * 8) = (u32x2){pk2(ov[0], ov[1]), pk2(ov[2], ov[3])};
;             }
	v_pk_mul_f32 v[18:19], v[72:73], v[18:19] op_sel_hi:[0,1]
	v_pk_fma_f32 v[18:19], v[26:27], v[66:67], v[18:19] op_sel_hi:[1,0,1]
	v_fma_f32 v26, -v24, v25, 1.0
	v_fmac_f32_e32 v25, v26, v25
	v_div_scale_f32 v26, vcc, v23, v21, v23
	v_mul_f32_e32 v27, v26, v25
	v_fma_f32 v34, -v24, v27, v26
	v_fmac_f32_e32 v27, v34, v25
	v_fma_f32 v24, -v24, v27, v26
	v_div_fmas_f32 v24, v24, v25, v27
	v_div_fixup_f32 v21, v24, v21, v23
	v_div_scale_f32 v23, s[0:1], v20, v20, v22
	v_rcp_f32_e32 v24, v23
	v_pk_mul_f32 v[18:19], v[0:1], v[18:19] op_sel_hi:[0,1]
	v_fma_f32 v25, -v23, v24, 1.0
	v_fmac_f32_e32 v24, v25, v24
	v_div_scale_f32 v25, vcc, v22, v20, v22
	v_mul_f32_e32 v26, v25, v24
	v_fma_f32 v27, -v23, v26, v25
	v_fmac_f32_e32 v26, v27, v24
	v_fma_f32 v23, -v23, v26, v25
	v_div_fmas_f32 v23, v23, v24, v26
	v_lshlrev_b32_e32 v24, 16, v171
	v_and_b32_e32 v25, 0xffff0000, v171
	v_div_fixup_f32 v20, v23, v20, v22
	v_mul_f32_e32 v22, 0xbfb8aa3b, v24
	v_mul_f32_e32 v23, 0xbfb8aa3b, v25
	v_exp_f32_e32 v22, v22
	v_exp_f32_e32 v23, v23
	v_pk_mul_f32 v[18:19], v[20:21], v[18:19]
	ds_read2st64_b32 v[20:21], v104 offset0:42 offset1:43
	v_cvt_pk_bf16_f32 v136, v18, v19
	v_pk_add_f32 v[22:23], v[22:23], 1.0 op_sel_hi:[1,0]
	s_waitcnt lgkmcnt(0)
	v_pk_mul_f32 v[20:21], v[72:73], v[20:21] op_sel_hi:[0,1]
	v_div_scale_f32 v26, s[0:1], v23, v23, v25
	v_rcp_f32_e32 v27, v26
	v_pk_fma_f32 v[20:21], v[28:29], v[66:67], v[20:21] op_sel_hi:[1,0,1]
	v_fma_f32 v28, -v26, v27, 1.0
	v_fmac_f32_e32 v27, v28, v27
	v_div_scale_f32 v28, vcc, v25, v23, v25
	v_mul_f32_e32 v29, v28, v27
	v_fma_f32 v34, -v26, v29, v28
	v_fmac_f32_e32 v29, v34, v27
	v_fma_f32 v26, -v26, v29, v28
	v_div_fmas_f32 v26, v26, v27, v29
	v_div_fixup_f32 v23, v26, v23, v25
	v_div_scale_f32 v25, s[0:1], v22, v22, v24
	v_rcp_f32_e32 v26, v25
	v_pk_mul_f32 v[20:21], v[0:1], v[20:21] op_sel_hi:[0,1]
	v_fma_f32 v27, -v25, v26, 1.0
	v_fmac_f32_e32 v26, v27, v26
	v_div_scale_f32 v27, vcc, v24, v22, v24
	v_mul_f32_e32 v28, v27, v26
	v_fma_f32 v29, -v25, v28, v27
	v_fmac_f32_e32 v28, v29, v26
	v_fma_f32 v25, -v25, v28, v27
	v_div_fmas_f32 v25, v25, v26, v28
	v_div_fixup_f32 v22, v25, v22, v24
	v_pk_mul_f32 v[20:21], v[22:23], v[20:21]
	v_lshlrev_b32_e32 v22, 16, v172
	v_and_b32_e32 v23, 0xffff0000, v172
	v_cvt_pk_bf16_f32 v137, v20, v21
	v_mul_f32_e32 v20, 0xbfb8aa3b, v22
	v_mul_f32_e32 v21, 0xbfb8aa3b, v23
	v_exp_f32_e32 v20, v20
	v_exp_f32_e32 v21, v21
	ds_read2st64_b32 v[18:19], v104 offset0:44 offset1:45
	v_pk_add_f32 v[20:21], v[20:21], 1.0 op_sel_hi:[1,0]
	s_nop 0
	v_div_scale_f32 v24, s[0:1], v21, v21, v23
	v_rcp_f32_e32 v25, v24
	s_waitcnt lgkmcnt(0)
	v_pk_mul_f32 v[18:19], v[72:73], v[18:19] op_sel_hi:[0,1]
	v_pk_fma_f32 v[18:19], v[30:31], v[66:67], v[18:19] op_sel_hi:[1,0,1]
	v_fma_f32 v26, -v24, v25, 1.0
	v_fmac_f32_e32 v25, v26, v25
	v_div_scale_f32 v26, vcc, v23, v21, v23
	v_mul_f32_e32 v27, v26, v25
	v_fma_f32 v28, -v24, v27, v26
	v_fmac_f32_e32 v27, v28, v25
	v_fma_f32 v24, -v24, v27, v26
	v_div_fmas_f32 v24, v24, v25, v27
	v_div_fixup_f32 v21, v24, v21, v23
	v_div_scale_f32 v23, s[0:1], v20, v20, v22
	v_rcp_f32_e32 v24, v23
	v_pk_mul_f32 v[18:19], v[0:1], v[18:19] op_sel_hi:[0,1]
	v_fma_f32 v25, -v23, v24, 1.0
	v_fmac_f32_e32 v24, v25, v24
	v_div_scale_f32 v25, vcc, v22, v20, v22
	v_mul_f32_e32 v26, v25, v24
	v_fma_f32 v27, -v23, v26, v25
	v_fmac_f32_e32 v26, v27, v24
	v_fma_f32 v23, -v23, v26, v25
	v_div_fmas_f32 v23, v23, v24, v26
	v_lshlrev_b32_e32 v24, 16, v173
	v_and_b32_e32 v25, 0xffff0000, v173
	v_div_fixup_f32 v20, v23, v20, v22
	v_mul_f32_e32 v22, 0xbfb8aa3b, v24
	v_mul_f32_e32 v23, 0xbfb8aa3b, v25
	v_exp_f32_e32 v22, v22
	v_exp_f32_e32 v23, v23
	v_pk_mul_f32 v[18:19], v[20:21], v[18:19]
	ds_read2st64_b32 v[20:21], v104 offset0:46 offset1:47
	v_cvt_pk_bf16_f32 v138, v18, v19
	v_pk_add_f32 v[22:23], v[22:23], 1.0 op_sel_hi:[1,0]
	s_waitcnt lgkmcnt(0)
	v_pk_mul_f32 v[20:21], v[72:73], v[20:21] op_sel_hi:[0,1]
	v_div_scale_f32 v26, s[0:1], v23, v23, v25
	v_rcp_f32_e32 v27, v26
	v_pk_fma_f32 v[20:21], v[32:33], v[66:67], v[20:21] op_sel_hi:[1,0,1]
	v_fma_f32 v28, -v26, v27, 1.0
	v_fmac_f32_e32 v27, v28, v27
	v_div_scale_f32 v28, vcc, v25, v23, v25
	v_mul_f32_e32 v29, v28, v27
	v_fma_f32 v30, -v26, v29, v28
	v_fmac_f32_e32 v29, v30, v27
	v_fma_f32 v26, -v26, v29, v28
	v_div_fmas_f32 v26, v26, v27, v29
	v_div_fixup_f32 v23, v26, v23, v25
	v_div_scale_f32 v25, s[0:1], v22, v22, v24
	v_rcp_f32_e32 v26, v25
	v_pk_mul_f32 v[20:21], v[0:1], v[20:21] op_sel_hi:[0,1]
	v_fma_f32 v27, -v25, v26, 1.0
	v_fmac_f32_e32 v26, v27, v26
	v_div_scale_f32 v27, vcc, v24, v22, v24
	v_mul_f32_e32 v28, v27, v26
	v_fma_f32 v29, -v25, v28, v27
	v_fmac_f32_e32 v28, v29, v26
	v_fma_f32 v25, -v25, v28, v27
	v_div_fmas_f32 v25, v25, v26, v28
	v_div_fixup_f32 v22, v25, v22, v24
	v_pk_mul_f32 v[20:21], v[22:23], v[20:21]
	v_lshlrev_b32_e32 v22, 16, v174
	v_cvt_pk_bf16_f32 v139, v20, v21
	s_nop 1
	v_permlane32_swap_b32_e32 v136, v138
	v_permlane32_swap_b32_e32 v137, v139
	global_store_dwordx4 v[148:149], v[136:139], off offset:160
	ds_read2st64_b32 v[18:19], v104 offset0:48 offset1:49
	v_and_b32_e32 v23, 0xffff0000, v174
	v_mul_f32_e32 v20, 0xbfb8aa3b, v22
	v_exp_f32_e32 v20, v20
	s_waitcnt lgkmcnt(0)
	v_pk_mul_f32 v[18:19], v[72:73], v[18:19] op_sel_hi:[0,1]
	v_pk_fma_f32 v[2:3], v[2:3], v[66:67], v[18:19] op_sel_hi:[1,0,1]
	v_mul_f32_e32 v18, 0xbfb8aa3b, v23
	v_exp_f32_e32 v21, v18
	v_pk_mul_f32 v[2:3], v[0:1], v[2:3] op_sel_hi:[0,1]
	v_pk_add_f32 v[18:19], v[20:21], 1.0 op_sel_hi:[1,0]
	s_nop 0
	v_rcp_f32_e32 v21, v19
	s_nop 0
	v_mul_f32_e32 v19, v23, v21
	v_rcp_f32_e32 v21, v18
	s_nop 0
	v_mul_f32_e32 v18, v22, v21
	v_pk_mul_f32 v[2:3], v[18:19], v[2:3]
	ds_read2st64_b32 v[18:19], v104 offset0:50 offset1:51
	v_lshlrev_b32_e32 v22, 16, v175
	v_and_b32_e32 v23, 0xffff0000, v175
	v_mul_f32_e32 v20, 0xbfb8aa3b, v22
	v_exp_f32_e32 v20, v20
	s_waitcnt lgkmcnt(0)
; DI unsigned pk2(float lo, float hi) { f32x2 v = {lo, hi}; return __builtin_bit_cast(unsigned, __builtin_convertvector(v, bf2_t)); }
; DI float bflo(unsigned w) { return __uint_as_float(w << 16); }
; DI float bfhi(unsigned w) { return __uint_as_float(w & 0xffff0000u); }
; DI void attn_unit(const Params& p, int b, int h, int qb, LAS unsigned char* lds, int tid, int lane, int wave) {
;     ...
; #pragma unroll
;         for (int i = 0; i < 4; ++i)
; #pragma unroll
;             for (int q = 0; q < 4; ++q) {
;                 float gv[4] = {bflo(gw[i][q].x), bfhi(gw[i][q].x), bflo(gw[i][q].y), bfhi(gw[i][q].y)}; float ov[4];
; #pragma unroll
;                 for (int e = 0; e < 4; ++e) { const float val = (o[i][q * 4 + e] * a0 + MB[(i * 16 + q * 4 + e) * 64] * a1) * inv; ov[e] = val * (gv[e] / (1.f + __expf(-gv[e]))); }
;                 *(u32x2*)(op + i * 32 + q * 8) = (u32x2){pk2(ov[0], ov[1]), pk2(ov[2], ov[3])};
;             }
	v_pk_mul_f32 v[18:19], v[72:73], v[18:19] op_sel_hi:[0,1]
	v_pk_fma_f32 v[4:5], v[4:5], v[66:67], v[18:19] op_sel_hi:[1,0,1]
	v_mul_f32_e32 v18, 0xbfb8aa3b, v23
	v_exp_f32_e32 v21, v18
	v_pk_mul_f32 v[4:5], v[0:1], v[4:5] op_sel_hi:[0,1]
	v_cvt_pk_bf16_f32 v140, v2, v3
	v_pk_add_f32 v[18:19], v[20:21], 1.0 op_sel_hi:[1,0]
	s_nop 0
	v_rcp_f32_e32 v21, v19
	s_nop 0
	v_mul_f32_e32 v19, v23, v21
	v_rcp_f32_e32 v21, v18
	s_nop 0
	v_mul_f32_e32 v18, v22, v21
	v_pk_mul_f32 v[4:5], v[18:19], v[4:5]
	v_lshlrev_b32_e32 v18, 16, v176
	v_cvt_pk_bf16_f32 v141, v4, v5
	v_and_b32_e32 v19, 0xffff0000, v176
	ds_read2st64_b32 v[2:3], v104 offset0:52 offset1:53
	v_mul_f32_e32 v4, 0xbfb8aa3b, v18
	v_mul_f32_e32 v5, 0xbfb8aa3b, v19
	v_exp_f32_e32 v4, v4
	v_exp_f32_e32 v5, v5
	s_waitcnt lgkmcnt(0)
	v_pk_mul_f32 v[2:3], v[72:73], v[2:3] op_sel_hi:[0,1]
	v_pk_fma_f32 v[2:3], v[6:7], v[66:67], v[2:3] op_sel_hi:[1,0,1]
	v_pk_add_f32 v[4:5], v[4:5], 1.0 op_sel_hi:[1,0]
	s_nop 0
	v_div_scale_f32 v6, s[0:1], v5, v5, v19
	v_rcp_f32_e32 v7, v6
	v_pk_mul_f32 v[2:3], v[0:1], v[2:3] op_sel_hi:[0,1]
	v_fma_f32 v20, -v6, v7, 1.0
	v_fmac_f32_e32 v7, v20, v7
	v_div_scale_f32 v20, vcc, v19, v5, v19
	v_mul_f32_e32 v21, v20, v7
	v_fma_f32 v22, -v6, v21, v20
	v_fmac_f32_e32 v21, v22, v7
	v_fma_f32 v6, -v6, v21, v20
	v_div_fmas_f32 v6, v6, v7, v21
	v_div_fixup_f32 v5, v6, v5, v19
	v_rcp_f32_e32 v7, v4
	s_nop 0
	v_mul_f32_e32 v4, v18, v7
	v_lshlrev_b32_e32 v18, 16, v177
	v_and_b32_e32 v19, 0xffff0000, v177
	v_pk_mul_f32 v[2:3], v[4:5], v[2:3]
	ds_read2st64_b32 v[4:5], v104 offset0:54 offset1:55
	v_mul_f32_e32 v6, 0xbfb8aa3b, v18
	v_mul_f32_e32 v7, 0xbfb8aa3b, v19
	v_exp_f32_e32 v6, v6
	v_exp_f32_e32 v7, v7
	s_waitcnt lgkmcnt(0)
	v_pk_mul_f32 v[4:5], v[72:73], v[4:5] op_sel_hi:[0,1]
	v_pk_fma_f32 v[4:5], v[8:9], v[66:67], v[4:5] op_sel_hi:[1,0,1]
	v_cvt_pk_bf16_f32 v142, v2, v3
	v_pk_add_f32 v[6:7], v[6:7], 1.0 op_sel_hi:[1,0]
	v_pk_mul_f32 v[4:5], v[0:1], v[4:5] op_sel_hi:[0,1]
	v_rcp_f32_e32 v9, v7
	s_nop 0
	v_mul_f32_e32 v7, v19, v9
	v_rcp_f32_e32 v9, v6
	s_nop 0
	v_mul_f32_e32 v6, v18, v9
	v_pk_mul_f32 v[4:5], v[6:7], v[4:5]
	v_lshlrev_b32_e32 v6, 16, v178
	v_and_b32_e32 v7, 0xffff0000, v178
	v_cvt_pk_bf16_f32 v143, v4, v5
	v_mul_f32_e32 v4, 0xbfb8aa3b, v6
	v_mul_f32_e32 v5, 0xbfb8aa3b, v7
	v_exp_f32_e32 v4, v4
	v_exp_f32_e32 v5, v5
	s_nop 1
	v_permlane32_swap_b32_e32 v140, v142
	v_permlane32_swap_b32_e32 v141, v143
	global_store_dwordx4 v[148:149], v[140:143], off offset:192
	ds_read2st64_b32 v[2:3], v104 offset0:56 offset1:57
	v_pk_add_f32 v[4:5], v[4:5], 1.0 op_sel_hi:[1,0]
	s_nop 0
	v_div_scale_f32 v8, s[0:1], v5, v5, v7
	v_rcp_f32_e32 v9, v8
	s_waitcnt lgkmcnt(0)
	v_pk_mul_f32 v[2:3], v[72:73], v[2:3] op_sel_hi:[0,1]
	v_pk_fma_f32 v[2:3], v[10:11], v[66:67], v[2:3] op_sel_hi:[1,0,1]
	v_fma_f32 v10, -v8, v9, 1.0
	v_fmac_f32_e32 v9, v10, v9
	v_div_scale_f32 v10, vcc, v7, v5, v7
	v_mul_f32_e32 v11, v10, v9
	v_fma_f32 v18, -v8, v11, v10
	v_fmac_f32_e32 v11, v18, v9
	v_fma_f32 v8, -v8, v11, v10
	v_div_fmas_f32 v8, v8, v9, v11
	v_div_fixup_f32 v5, v8, v5, v7
	v_div_scale_f32 v7, s[0:1], v4, v4, v6
	v_rcp_f32_e32 v8, v7
	v_pk_mul_f32 v[2:3], v[0:1], v[2:3] op_sel_hi:[0,1]
	v_fma_f32 v9, -v7, v8, 1.0
	v_fmac_f32_e32 v8, v9, v8
	v_div_scale_f32 v9, vcc, v6, v4, v6
	v_mul_f32_e32 v10, v9, v8
	v_fma_f32 v11, -v7, v10, v9
	v_fmac_f32_e32 v10, v11, v8
	v_fma_f32 v7, -v7, v10, v9
	v_div_fmas_f32 v7, v7, v8, v10
	v_lshlrev_b32_e32 v8, 16, v179
	v_and_b32_e32 v9, 0xffff0000, v179
	v_div_fixup_f32 v4, v7, v4, v6
	v_mul_f32_e32 v6, 0xbfb8aa3b, v8
	v_mul_f32_e32 v7, 0xbfb8aa3b, v9
	v_exp_f32_e32 v6, v6
	v_exp_f32_e32 v7, v7
	v_pk_mul_f32 v[2:3], v[4:5], v[2:3]
	ds_read2st64_b32 v[4:5], v104 offset0:58 offset1:59
	v_cvt_pk_bf16_f32 v144, v2, v3
	v_pk_add_f32 v[6:7], v[6:7], 1.0 op_sel_hi:[1,0]
	s_waitcnt lgkmcnt(0)
	v_pk_mul_f32 v[4:5], v[72:73], v[4:5] op_sel_hi:[0,1]
	v_div_scale_f32 v10, s[0:1], v7, v7, v9
	v_rcp_f32_e32 v11, v10
	v_pk_fma_f32 v[4:5], v[12:13], v[66:67], v[4:5] op_sel_hi:[1,0,1]
	v_fma_f32 v12, -v10, v11, 1.0
	v_fmac_f32_e32 v11, v12, v11
	v_div_scale_f32 v12, vcc, v9, v7, v9
	v_mul_f32_e32 v13, v12, v11
	v_fma_f32 v18, -v10, v13, v12
	v_fmac_f32_e32 v13, v18, v11
	v_fma_f32 v10, -v10, v13, v12
	v_div_fmas_f32 v10, v10, v11, v13
	v_div_fixup_f32 v7, v10, v7, v9
	v_div_scale_f32 v9, s[0:1], v6, v6, v8
	v_rcp_f32_e32 v10, v9
	v_pk_mul_f32 v[4:5], v[0:1], v[4:5] op_sel_hi:[0,1]
	v_fma_f32 v11, -v9, v10, 1.0
	v_fmac_f32_e32 v10, v11, v10
	v_div_scale_f32 v11, vcc, v8, v6, v8
	v_mul_f32_e32 v12, v11, v10
	v_fma_f32 v13, -v9, v12, v11
	v_fmac_f32_e32 v12, v13, v10
	v_fma_f32 v9, -v9, v12, v11
	v_div_fmas_f32 v9, v9, v10, v12
	v_div_fixup_f32 v6, v9, v6, v8
	v_pk_mul_f32 v[4:5], v[6:7], v[4:5]
	v_lshlrev_b32_e32 v6, 16, v180
	v_and_b32_e32 v7, 0xffff0000, v180
	v_cvt_pk_bf16_f32 v145, v4, v5
	v_mul_f32_e32 v4, 0xbfb8aa3b, v6
	v_mul_f32_e32 v5, 0xbfb8aa3b, v7
	v_exp_f32_e32 v4, v4
	v_exp_f32_e32 v5, v5
	ds_read2st64_b32 v[2:3], v104 offset0:60 offset1:61
	v_pk_add_f32 v[4:5], v[4:5], 1.0 op_sel_hi:[1,0]
	s_nop 0
	v_div_scale_f32 v8, s[0:1], v5, v5, v7
	v_rcp_f32_e32 v9, v8
	s_waitcnt lgkmcnt(0)
	v_pk_mul_f32 v[2:3], v[72:73], v[2:3] op_sel_hi:[0,1]
	v_pk_fma_f32 v[2:3], v[14:15], v[66:67], v[2:3] op_sel_hi:[1,0,1]
	v_fma_f32 v10, -v8, v9, 1.0
	v_fmac_f32_e32 v9, v10, v9
	v_div_scale_f32 v10, vcc, v7, v5, v7
	v_mul_f32_e32 v11, v10, v9
	v_fma_f32 v12, -v8, v11, v10
	v_fmac_f32_e32 v11, v12, v9
	v_fma_f32 v8, -v8, v11, v10
	v_div_fmas_f32 v8, v8, v9, v11
	v_div_fixup_f32 v5, v8, v5, v7
	v_div_scale_f32 v7, s[0:1], v4, v4, v6
	v_rcp_f32_e32 v8, v7
	v_pk_mul_f32 v[2:3], v[0:1], v[2:3] op_sel_hi:[0,1]
	v_fma_f32 v9, -v7, v8, 1.0
	v_fmac_f32_e32 v8, v9, v8
	v_div_scale_f32 v9, vcc, v6, v4, v6
	v_mul_f32_e32 v10, v9, v8
	v_fma_f32 v11, -v7, v10, v9
	v_fmac_f32_e32 v10, v11, v8
	v_fma_f32 v7, -v7, v10, v9
	v_div_fmas_f32 v7, v7, v8, v10
	v_div_fixup_f32 v4, v7, v4, v6
	v_pk_mul_f32 v[2:3], v[4:5], v[2:3]
	ds_read2st64_b32 v[4:5], v104 offset0:62 offset1:63
	v_lshlrev_b32_e32 v8, 16, v181
	v_and_b32_e32 v9, 0xffff0000, v181
	v_mul_f32_e32 v6, 0xbfb8aa3b, v8
	v_exp_f32_e32 v6, v6
	s_waitcnt lgkmcnt(0)
	v_pk_mul_f32 v[4:5], v[72:73], v[4:5] op_sel_hi:[0,1]
	v_pk_fma_f32 v[4:5], v[16:17], v[66:67], v[4:5] op_sel_hi:[1,0,1]
	v_cvt_pk_bf16_f32 v146, v2, v3
	v_pk_mul_f32 v[4:5], v[0:1], v[4:5] op_sel_hi:[0,1]
	v_mul_f32_e32 v0, 0xbfb8aa3b, v9
	v_exp_f32_e32 v7, v0
	s_nop 0
	v_pk_add_f32 v[6:7], v[6:7], 1.0 op_sel_hi:[1,0]
	s_nop 0
	v_rcp_f32_e32 v10, v7
	s_nop 0
	v_mul_f32_e32 v7, v9, v10
	v_rcp_f32_e32 v9, v6
	s_nop 0
	v_mul_f32_e32 v6, v8, v9
	v_pk_mul_f32 v[4:5], v[6:7], v[4:5]
	s_nop 0
	v_cvt_pk_bf16_f32 v147, v4, v5
	s_nop 1
	v_permlane32_swap_b32_e32 v144, v146
	v_permlane32_swap_b32_e32 v145, v147
	global_store_dwordx4 v[148:149], v[144:147], off offset:224
	s_branch .LBB0_425
